# own P5 epilogue codegen with row-permuted A staging (layout B: conv row shifts mostly in-lane, fewer DPP), gelu via max+fma, on top of v14
# speedup vs baseline: 1.0421x; 1.0192x over previous
; #define PG8_STAGE(bufoff, gbase, voff) do { _Pragma("unroll") for (int _i = 0; _i < 2; ++_i) \
;         __builtin_amdgcn_global_load_lds((const unsigned*)((const char*)(gbase) + (voff)[_i]), (LAS unsigned*)(lds + (bufoff) + ldsw + _i * 8192), 16, 0, 0); } while (0)
; #define PG8_WAIT_V(n) asm volatile("s_waitcnt vmcnt(" #n ")" ::: "memory")
; #define PG8_BAR __builtin_amdgcn_s_barrier()
;     __device__ __forceinline__ bool next(int i, Unit& u) const { u.z = 0; return o.tile(i, u); }
; template <class Epi, class Sched>
; __device__ __forceinline__ void gemm_phase(LAS unsigned char* lds, const Gemm g, const Sched& S, const Epi& E) {
;     int tid = threadIdx.x; asm volatile("" : "+v"(tid));
;     const int wid = __builtin_amdgcn_readfirstlane(tid >> 6), lane = tid & 63, wr = wid >> 2, wc = wid & 3, fr = lane & 15, fq = lane >> 4;
;     const int K = g.K, nt = K / BK;
;     unsigned voffA[2], voffB[2];
; #pragma unroll
;     for (int i = 0; i < 2; ++i) { int R, C; stage_rc(tid * 16 + i * 8192, R, C); const int Rb = Epi::PERM ? ((R & ~31) + perm32(R & 31)) : R;
;         voffA[i] = (unsigned)(R * g.lda + C) * 2u; voffB[i] = (unsigned)(Rb * g.ldb + C) * 2u; }
;     const size_t kstep = (size_t)(BK * 2);
;     const size_t hstepA = (size_t)HALF * g.lda * 2, hstepB = (size_t)HALF * g.ldb * 2;
;     const unsigned ldsw = (unsigned)wid * 1024u;
;     const int aoff = lds_byte(wr * 64 + fr, fq * 8), boff = lds_byte(wc * 32 + fr, fq * 8);
;     ...
;     Unit cur, nxt; int ui = 0;
;     if (!S.next(0, cur)) return;
;     f32x4 acc[2][2][4][2];
; #pragma unroll
;     for (int a = 0; a < 2; ++a)
; #pragma unroll
;         for (int b = 0; b < 2; ++b)
; #pragma unroll
;             for (int m = 0; m < 4; ++m)
; #pragma unroll
;                 for (int n = 0; n < 2; ++n) acc[a][b][m][n] = (f32x4){0.f, 0.f, 0.f, 0.f};
;     bf16x8 At[4][2], B0[2][2], B1[2][2];
;     const char* cA = (const char*)g.A + S.a_off(cur); const char* cB = (const char*)g.Bt + S.b_off(cur);
;     PG8_STAGE(PG8_SB(0, 0), cB, voffB); PG8_STAGE(PG8_SB(0, 1), cB + hstepB, voffB); PG8_STAGE(PG8_SA(0, 0), cA, voffA); PG8_STAGE(PG8_SA(0, 1), cA + hstepA, voffA);
;     if (wr == 1) PG8_BAR;
;     PG8_WAIT_V(2); PG8_BAR;
;     PG8_STAGE(PG8_SB(1, 0), cB + kstep, voffB); PG8_STAGE(PG8_SA(1, 0), cA + kstep, voffA); PG8_STAGE(PG8_SB(1, 1), cB + hstepB + kstep, voffB);
;     PG8_WAIT_V(6); PG8_BAR;
.LBB0_1016:
	v_readlane_b32 s0, v247, 14
	s_add_u32 s92, s86, 0x1ce00000
	v_mov_b32_e32 v14, v222
	v_readlane_b32 s1, v247, 15
	s_addc_u32 s93, s87, 0
	s_andn2_b64 vcc, exec, s[0:1]
	v_readfirstlane_b32 s3, v14
	s_cbranch_vccnz .LBB0_1122
	v_lshlrev_b32_e32 v0, 4, v14
	v_add_u32_e32 v1, 0x2000, v0
	v_ashrrev_i32_e32 v2, 31, v1
	v_lshrrev_b32_e32 v2, 22, v2
	v_add_u32_e32 v2, v1, v2
	v_ashrrev_i32_e32 v8, 10, v2
	v_mul_i32_i24_e32 v2, 0x400, v8
	v_sub_u32_e32 v1, v1, v2
	v_lshrrev_b32_e32 v2, 4, v1
	v_bitop3_b32 v1, v2, v1, 32 bitop3:0x6c
	v_ashrrev_i32_e32 v2, 31, v1
	v_lshrrev_b32_e32 v2, 26, v2
	s_ashr_i32 s0, s3, 6
	v_add_u32_e32 v2, v1, v2
	v_lshlrev_b32_e32 v3, 3, v8
	s_ashr_i32 s2, s3, 8
	s_lshl_b32 s29, s0, 10
	v_readlane_b32 s1, v246, 16
	v_ashrrev_i32_e32 v9, 6, v2
	v_and_b32_e32 v3, -16, v3
	s_add_u32 s7, s1, 0xa80000
	v_readlane_b32 s1, v246, 17
	v_add_u32_e32 v3, v9, v3
	s_addc_u32 s10, s1, 0
	v_and_b32_e32 v4, 3, v9
	s_mov_b32 s1, 0x1fffe0
	v_lshrrev_b32_e32 v5, 2, v3
	v_lshlrev_b32_e32 v6, 1, v3
	v_and_b32_e32 v2, 0xc0, v2
	v_and_or_b32 v4, v3, s1, v4
	v_and_b32_e32 v5, 4, v5
	v_and_b32_e32 v6, 24, v6
	v_sub_u32_e32 v1, v1, v2
	v_or3_b32 v4, v4, v5, v6
	v_lshlrev_b32_e32 v5, 5, v8
	v_ashrrev_i16_sdwa v1, v224, sext(v1) dst_sel:DWORD dst_unused:UNUSED_PAD src0_sel:DWORD src1_sel:BYTE_0
	v_and_b32_e32 v5, 32, v5
	v_bfe_i32 v10, v1, 0, 16
	v_add_lshl_u32 v1, v5, v10, 1
	v_lshl_add_u32 v172, v4, 11, v1
	v_lshl_add_u32 v174, v3, 11, v1
	v_bfe_i32 v1, v14, 27, 1
	v_lshrrev_b32_e32 v1, 22, v1
	v_add_u32_e32 v1, v0, v1
	v_and_b32_e32 v1, 0xfffffc00, v1
	v_sub_u32_e32 v0, v0, v1
	v_lshrrev_b32_e32 v1, 4, v0
	v_ashrrev_i32_e32 v2, 31, v14
	v_bitop3_b32 v0, v1, v0, 32 bitop3:0x6c
	v_lshrrev_b32_e32 v2, 26, v2
	v_ashrrev_i32_e32 v1, 31, v0
	v_add_u32_e32 v2, v14, v2
	v_lshrrev_b32_e32 v1, 26, v1
	v_ashrrev_i32_e32 v12, 6, v2
	v_add_u32_e32 v1, v0, v1
	v_lshlrev_b32_e32 v2, 3, v12
	v_ashrrev_i32_e32 v11, 6, v1
	v_and_b32_e32 v2, -16, v2
	v_add_u32_e32 v2, v11, v2
	v_and_b32_e32 v3, 3, v11
	v_lshrrev_b32_e32 v4, 2, v2
	v_lshlrev_b32_e32 v5, 1, v2
	v_and_b32_e32 v1, 0xc0, v1
	v_and_or_b32 v3, v2, s1, v3
	v_and_b32_e32 v4, 4, v4
	v_and_b32_e32 v5, 24, v5
	v_sub_u32_e32 v0, v0, v1
	v_or3_b32 v3, v3, v4, v5
	v_lshlrev_b32_e32 v4, 5, v12
	v_ashrrev_i16_sdwa v0, v224, sext(v0) dst_sel:DWORD dst_unused:UNUSED_PAD src0_sel:DWORD src1_sel:BYTE_0
	v_readlane_b32 s8, v247, 43
	v_and_b32_e32 v4, 32, v4
	v_bfe_i32 v13, v0, 0, 16
	v_readlane_b32 s9, v247, 44
	s_add_u32 s14, s7, s8
	v_add_lshl_u32 v0, v4, v13, 1
	s_addc_u32 s15, s10, s9
	s_add_i32 s25, s29, 0
	v_lshl_add_u32 v96, v3, 11, v0
	s_add_i32 m0, s25, 0x10000
	v_lshrrev_b32_e32 v176, 1, v12
	v_lshl_add_u32 v176, v11, 2, v176
	v_lshl_add_u32 v176, v176, 11, v0
	v_add_u32_e32 v174, 0x20000, v176
	global_load_lds_dwordx4 v96, s[14:15]
	s_add_i32 m0, s25, 0x12000
	s_add_u32 s8, s14, 0x40000
	global_load_lds_dwordx4 v172, s[14:15]
	s_addc_u32 s9, s15, 0
	s_add_i32 m0, s25, 0x14000
	v_writelane_b32 v246, s7, 26
	global_load_lds_dwordx4 v96, s[8:9]
	s_add_i32 m0, s25, 0x16000
	v_writelane_b32 v246, s10, 27
	global_load_lds_dwordx4 v172, s[8:9]
	v_readlane_b32 s8, v247, 41
	v_readlane_b32 s9, v247, 42
	s_add_u32 s18, s90, s8
	s_addc_u32 s19, s91, s9
	s_add_i32 s27, s25, 0x2000
	s_mov_b32 m0, s25
	s_add_u32 s8, s18, 0x40000
	global_load_lds_dwordx4 v176, s[18:19]
	s_mov_b32 m0, s27
	s_addc_u32 s9, s19, 0
	s_add_i32 s37, s25, 0x4000
	global_load_lds_dwordx4 v174, s[18:19]
	s_mov_b32 m0, s37
	s_add_i32 s33, s25, 0x6000
	global_load_lds_dwordx4 v176, s[8:9]
	s_mov_b32 m0, s33
	s_cmp_eq_u32 s2, 1
	global_load_lds_dwordx4 v174, s[8:9]
	v_mov_b32_e32 v173, v97
	v_mov_b32_e32 v177, v97
	v_mov_b32_e32 v175, v97
	s_cselect_b64 s[8:9], -1, 0
	v_lshl_add_u64 v[4:5], s[14:15], 0, v[96:97]
	v_lshl_add_u64 v[2:3], s[14:15], 0, v[172:173]
	v_lshl_add_u64 v[0:1], s[18:19], 0, v[176:177]
	v_writelane_b32 v246, s8, 28
	s_cmp_lg_u32 s2, 1
	v_lshl_add_u64 v[6:7], s[18:19], 0, v[174:175]
	v_writelane_b32 v246, s9, 29
	s_cbranch_scc1 .LBB0_1019
	s_barrier
.LBB0_1019:
	v_bfe_u32 v230, v14, 4, 2
	s_lshl_b32 s0, s0, 5
	v_and_b32_e32 v229, 15, v14
	s_lshl_b32 s1, s2, 6
	v_lshlrev_b32_e32 v15, 4, v230
	v_lshlrev_b32_e32 v14, 2, v14
	s_and_b32 s10, s0, 0x60
	v_writelane_b32 v246, s1, 30
	v_lshl_or_b32 v15, v229, 6, v15
	s_lshl_b32 s1, s2, 13
	v_and_b32_e32 v14, 32, v14
	s_lshl_b32 s0, s10, 7
	v_bitop3_b32 v16, v15, s1, v14 bitop3:0xde
	v_bitop3_b32 v231, v15, s0, v14 bitop3:0xde
	v_readlane_b32 s0, v246, 11
	v_readlane_b32 s1, v246, 12
	s_add_u32 s0, s0, s96
	s_addc_u32 s1, s1, 0
	s_add_u32 s0, s0, 0x811e000
	s_addc_u32 s1, s1, 0
	s_add_i32 m0, s25, 0x18000
	v_lshl_add_u64 v[4:5], v[4:5], 0, s[4:5]
	s_waitcnt vmcnt(2)
	s_barrier
	global_load_lds_dwordx4 v[4:5], off
	v_lshl_add_u64 v[2:3], v[2:3], 0, s[4:5]
	s_add_i32 m0, s25, 0x1a000
	s_add_i32 s96, s25, 0x8000
	s_add_i32 s7, s25, 0xa000
	global_load_lds_dwordx4 v[2:3], off
	v_lshl_add_u64 v[0:1], v[0:1], 0, s[4:5]
	s_mov_b32 m0, s96
	s_add_u32 s8, s14, 0x40080
	global_load_lds_dwordx4 v[0:1], off
	v_lshl_add_u64 v[0:1], v[6:7], 0, s[4:5]
	s_mov_b32 m0, s7
	s_addc_u32 s9, s15, 0
	global_load_lds_dwordx4 v[0:1], off
	s_add_i32 m0, s25, 0x1c000
	v_lshl_add_u64 v[0:1], s[8:9], 0, v[96:97]
	global_load_lds_dwordx4 v[0:1], off
	v_lshl_add_u64 v[0:1], s[8:9], 0, v[172:173]
	s_add_i32 m0, s25, 0x1e000
	s_cmpk_lt_u32 s3, 0x100
	global_load_lds_dwordx4 v[0:1], off
	s_cselect_b64 s[8:9], -1, 0
	s_lshl_b32 s3, s2, 1
	v_writelane_b32 v246, s8, 31
	s_add_i32 s3, s3, 0x3ffff2
	s_cmp_gt_i32 s2, 0
	v_writelane_b32 v246, s9, 32
	v_writelane_b32 v246, s3, 33
	s_cselect_b64 s[8:9], -1, 0
	s_lshl_b32 s3, s2, 11
	v_writelane_b32 v246, s8, 34
	s_cmp_gt_i32 s2, -2
	v_lshlrev_b32_e32 v0, 14, v8
	v_writelane_b32 v246, s9, 35
	s_cselect_b64 s[8:9], -1, 0
	v_and_b32_e32 v0, 0xffff8000, v0
	v_writelane_b32 v246, s8, 36
	s_lshl_b32 s2, s10, 2
	v_lshl_add_u32 v0, v9, 11, v0
	v_and_b32_e32 v1, 1, v8
	v_writelane_b32 v246, s9, 37
	s_add_i32 s8, s2, 0
	v_lshl_or_b32 v0, v1, 6, v0
	v_writelane_b32 v246, s10, 38
	s_add_i32 s8, s8, 0x21000
	v_mov_b32_e32 v178, v174
	v_lshlrev_b32_e32 v0, 14, v12
	v_writelane_b32 v246, s8, 39
	s_add_i32 s8, 0, 0x20000
	v_and_b32_e32 v0, 0xffff8000, v0
	s_waitcnt vmcnt(6)
	s_add_i32 s3, s8, s3
	v_lshl_add_u32 v0, v11, 11, v0
	v_and_b32_e32 v1, 1, v12
	s_add_i32 s3, s3, s2
	v_lshl_or_b32 v0, v1, 6, v0
	s_mov_b32 s31, 0
	v_writelane_b32 v246, s3, 40
	s_add_i32 s2, s8, s2
	v_mov_b32_e32 v179, v97
	v_mov_b32_e32 v180, v176
	v_mov_b32_e32 v181, v97
	v_add_u32_e32 v232, 0, v16
	v_readlane_b32 s22, v247, 32
	v_readlane_b32 s16, v247, 39
	s_barrier
	v_writelane_b32 v246, s2, 41
	v_readlane_b32 s17, v247, 40
	s_branch .LBB0_1022

;     __device__ __forceinline__ void operator()(AccT& acc, const Unit& u, int wr, int wc, int fr, int fq) const {
;         const int b = u.pm >> 6, tstart = (u.pm & 63) * 256;
;         const long arow0 = (long)u.pm * 256;
;         const int colg0 = u.pn * 128 + wc * 32 + fq * 8;
;         f32x4 cwg[2][3], cwv[2][3], cbg[2], cbv[2];
; #pragma unroll
;         for (int n = 0; n < 1; ++n) { const int colg = colg0 + n * 4, colv = FF + colg;
; #pragma unroll
;             for (int j = 0; j < 3; ++j) { cwg[n][j] = *(const f32x4*)(cw + j * FF2 + colg); cwv[n][j] = *(const f32x4*)(cw + j * FF2 + colv); }
;             cbg[n] = *(const f32x4*)(cb + colg); cbv[n] = *(const f32x4*)(cb + colv); }
;         float sq[2][4];
; #pragma unroll
;         for (int ai = 0; ai < 2; ++ai)
; #pragma unroll
;             for (int m = 0; m < 4; ++m) { const int rl = ai * 128 + wr * 64 + m * 16 + fr, t = tstart + rl; sq[ai][m] = ssq[arow0 + rl]; }
; #pragma unroll
;         for (int ai = 0; ai < 2; ++ai)
; #pragma unroll
;             for (int m = 0; m < 4; ++m) {
;                 const int rl = ai * 128 + wr * 64 + m * 16 + fr;
;                 const int t = tstart + rl;
;                 const float rs = __builtin_amdgcn_rsqf(sq[ai][m] * (1.0f / 1024.0f) + EPS);
; #pragma unroll
;                 for (int bj = 0; bj < 2; ++bj)
; #pragma unroll
;                     for (int n = 0; n < 2; ++n) acc[ai][bj][m][n] = acc[ai][bj][m][n] * rs;
;             }
.LBB0_1028:
	s_lshl_b32 s3, s22, 7
	v_readlane_b32 s9, v246, 38
	s_ashr_i32 s17, s16, 31
	v_readlane_b32 s18, v246, 20
	v_readlane_b32 s19, v246, 21
	v_readlane_b32 s20, v246, 30
	s_or_b32 s3, s3, s9
	v_lshlrev_b32_e32 v182, 3, v230
	v_mov_b32_e32 v183, 0
	v_mov_b32_e32 v193, 0
	v_add_u32_e32 v182, s3, v182
	s_lshl_b64 s[14:15], s[16:17], 10
	v_lshl_add_u32 v192, v229, 2, s20
	s_add_u32 s14, s18, s14
	s_addc_u32 s15, s19, s15
	v_lshl_add_u64 v[126:127], v[192:193], 2, s[14:15]
	global_load_dword v206, v[126:127], off
	global_load_dword v207, v[126:127], off offset:4
	global_load_dword v208, v[126:127], off offset:8
	global_load_dword v209, v[126:127], off offset:12
	global_load_dword v210, v[126:127], off offset:512
	global_load_dword v211, v[126:127], off offset:516
	global_load_dword v212, v[126:127], off offset:520
	global_load_dword v213, v[126:127], off offset:524
	v_cmp_eq_u32_e64 s[48:49], 0, v229
	v_cmp_eq_u32_e64 s[50:51], 15, v229
	s_cmp_eq_u32 s20, 0
	s_cselect_b64 s[54:55], -1, 0
	s_cselect_b64 s[72:73], 0, -1
	s_mov_b64 s[52:53], 0x2000
	s_and_b64 s[74:75], s[48:49], s[54:55]
	s_and_b64 s[76:77], s[50:51], s[72:73]
	s_and_b64 s[80:81], s[48:49], s[72:73]
	v_lshlrev_b64 v[126:127], 2, v[182:183]
	v_lshl_add_u64 v[214:215], s[44:45], 0, v[126:127]
	global_load_dwordx4 v[98:101], v[214:215], off
	v_lshl_add_u64 v[214:215], v[214:215], 0, s[52:53]
	global_load_dwordx4 v[84:87], v[214:215], off offset:3072
	v_lshl_add_u64 v[214:215], s[40:41], 0, v[126:127]
	global_load_dwordx4 v[102:105], v[214:215], off
	v_lshl_add_u64 v[214:215], v[214:215], 0, s[52:53]
	global_load_dwordx4 v[92:95], v[214:215], off offset:3072
	v_lshl_add_u64 v[214:215], s[42:43], 0, v[126:127]
	global_load_dwordx4 v[106:109], v[214:215], off
	v_lshl_add_u64 v[214:215], v[214:215], 0, s[52:53]
	global_load_dwordx4 v[88:91], v[214:215], off offset:3072
	v_lshl_add_u64 v[214:215], s[94:95], 0, v[126:127]
	global_load_dwordx4 v[110:113], v[214:215], off
	v_lshl_add_u64 v[214:215], v[214:215], 0, s[52:53]
	global_load_dwordx4 v[80:83], v[214:215], off offset:3072
	s_lshl_b64 s[16:17], s[16:17], 8
	v_lshl_add_u64 v[184:185], s[16:17], 0, v[192:193]
	v_mov_b64_e32 v[216:217], s[84:85]
	s_movk_i32 s3, 0x1600
	v_mad_u64_u32 v[216:217], s[22:23], v184, s3, v[216:217]
	v_mad_i32_i24 v217, v185, s3, v217
	v_lshl_add_u64 v[184:185], v[182:183], 1, v[216:217]
	s_mov_b32 s56, 0
	s_mov_b32 s57, 0
	s_mov_b32 s58, 5632
	s_mov_b32 s59, 0
	s_mov_b32 s60, 11264
	s_mov_b32 s61, 0
	s_mov_b32 s62, 16896
	s_mov_b32 s63, 0
	s_mov_b32 s64, 720896
	s_mov_b32 s65, 0
	s_mov_b32 s66, 726528
	s_mov_b32 s67, 0
	s_mov_b32 s68, 732160
	s_mov_b32 s69, 0
	s_mov_b32 s70, 737792
	s_mov_b32 s71, 0
	s_lshl_b32 s3, s20, 5
	s_lshl_b32 s9, s9, 4
	s_add_i32 s3, s3, s9
	s_add_i32 s3, s3, 0x20000
	v_lshl_add_u32 v189, v230, 7, s3
	v_add_u32_e32 v188, 0xfffff800, v189
	v_mov_b32_e32 v186, 0xbf3a00e3
	s_waitcnt vmcnt(0)
	v_fmamk_f32 v126, v206, 0x3a800000, v223
	v_rsq_f32_e32 v126, v126
	s_nop 0
	v_pk_mul_f32 v[160:161], v[160:161], v[126:127] op_sel_hi:[1,0]
	v_pk_mul_f32 v[162:163], v[162:163], v[126:127] op_sel_hi:[1,0]
	v_pk_mul_f32 v[60:61], v[60:61], v[126:127] op_sel_hi:[1,0]
	v_pk_mul_f32 v[62:63], v[62:63], v[126:127] op_sel_hi:[1,0]
	v_pk_mul_f32 v[156:157], v[156:157], v[126:127] op_sel_hi:[1,0]
	v_pk_mul_f32 v[158:159], v[158:159], v[126:127] op_sel_hi:[1,0]
	v_pk_mul_f32 v[56:57], v[56:57], v[126:127] op_sel_hi:[1,0]
	v_pk_mul_f32 v[58:59], v[58:59], v[126:127] op_sel_hi:[1,0]
	v_fmamk_f32 v126, v207, 0x3a800000, v223
	v_rsq_f32_e32 v126, v126
	s_nop 0
	v_pk_mul_f32 v[144:145], v[144:145], v[126:127] op_sel_hi:[1,0]
	v_pk_mul_f32 v[146:147], v[146:147], v[126:127] op_sel_hi:[1,0]
	v_pk_mul_f32 v[52:53], v[52:53], v[126:127] op_sel_hi:[1,0]
	v_pk_mul_f32 v[54:55], v[54:55], v[126:127] op_sel_hi:[1,0]
	v_pk_mul_f32 v[118:119], v[118:119], v[126:127] op_sel_hi:[1,0]
	v_pk_mul_f32 v[120:121], v[120:121], v[126:127] op_sel_hi:[1,0]
	v_pk_mul_f32 v[40:41], v[40:41], v[126:127] op_sel_hi:[1,0]
	v_pk_mul_f32 v[42:43], v[42:43], v[126:127] op_sel_hi:[1,0]
	v_fmamk_f32 v126, v208, 0x3a800000, v223
	v_rsq_f32_e32 v126, v126
	s_nop 0
	v_pk_mul_f32 v[140:141], v[140:141], v[126:127] op_sel_hi:[1,0]
	v_pk_mul_f32 v[142:143], v[142:143], v[126:127] op_sel_hi:[1,0]
	v_pk_mul_f32 v[36:37], v[36:37], v[126:127] op_sel_hi:[1,0]
	v_pk_mul_f32 v[38:39], v[38:39], v[126:127] op_sel_hi:[1,0]
	v_pk_mul_f32 v[114:115], v[114:115], v[126:127] op_sel_hi:[1,0]
	v_pk_mul_f32 v[116:117], v[116:117], v[126:127] op_sel_hi:[1,0]
	v_pk_mul_f32 v[32:33], v[32:33], v[126:127] op_sel_hi:[1,0]
	v_pk_mul_f32 v[34:35], v[34:35], v[126:127] op_sel_hi:[1,0]
	v_fmamk_f32 v126, v209, 0x3a800000, v223
	v_rsq_f32_e32 v126, v126
	s_nop 0
	v_pk_mul_f32 v[152:153], v[152:153], v[126:127] op_sel_hi:[1,0]
	v_pk_mul_f32 v[154:155], v[154:155], v[126:127] op_sel_hi:[1,0]
	v_pk_mul_f32 v[48:49], v[48:49], v[126:127] op_sel_hi:[1,0]
	v_pk_mul_f32 v[50:51], v[50:51], v[126:127] op_sel_hi:[1,0]
	v_pk_mul_f32 v[148:149], v[148:149], v[126:127] op_sel_hi:[1,0]
	v_pk_mul_f32 v[150:151], v[150:151], v[126:127] op_sel_hi:[1,0]
	v_pk_mul_f32 v[44:45], v[44:45], v[126:127] op_sel_hi:[1,0]
	v_pk_mul_f32 v[46:47], v[46:47], v[126:127] op_sel_hi:[1,0]
	v_fmamk_f32 v126, v210, 0x3a800000, v223
	v_rsq_f32_e32 v126, v126
	s_nop 0
	v_pk_mul_f32 v[136:137], v[136:137], v[126:127] op_sel_hi:[1,0]
	v_pk_mul_f32 v[138:139], v[138:139], v[126:127] op_sel_hi:[1,0]
	v_pk_mul_f32 v[28:29], v[28:29], v[126:127] op_sel_hi:[1,0]
	v_pk_mul_f32 v[30:31], v[30:31], v[126:127] op_sel_hi:[1,0]
	v_pk_mul_f32 v[132:133], v[132:133], v[126:127] op_sel_hi:[1,0]
;     __device__ __forceinline__ void operator()(AccT& acc, const Unit& u, int wr, int wc, int fr, int fq) const {
;     ...
;                     for (int n = 0; n < 2; ++n) acc[ai][bj][m][n] = acc[ai][bj][m][n] * rs;
;             }
;         if (fr >= 14) {
; #pragma unroll
;             for (int ai = 0; ai < 2; ++ai)
; #pragma unroll
;                 for (int bj = 0; bj < 2; ++bj)
; #pragma unroll
;                     for (int n = 0; n < 2; ++n)
;                         *(LAS f32x4*)(xch + (((ai * 2 + wr) * 2 + (fr - 14)) * 256 + bj * 128 + wc * 32 + fq * 8 + n * 4)) = acc[ai][bj][3][n];
;         }
;         asm volatile("s_waitcnt lgkmcnt(0)" ::: "memory"); __builtin_amdgcn_s_barrier(); asm volatile("" ::: "memory");
;         u32x2 stash[2][4];
; #pragma unroll
;         for (int n = 0; n < 2; ++n) {
;             const int colg = colg0 + n * 4, colv = FF + colg;
;             if (n == 1) {
; #pragma unroll
;                 for (int j = 0; j < 3; ++j) { cwg[1][j] = *(const f32x4*)(cw + j * FF2 + colg); cwv[1][j] = *(const f32x4*)(cw + j * FF2 + colv); }
;                 cbg[1] = *(const f32x4*)(cb + colg); cbv[1] = *(const f32x4*)(cb + colv); }
;             const f32x4 w0g = cwg[n][0], w1g = cwg[n][1], w2g = cwg[n][2], bg = cbg[n];
;             const f32x4 w0v = cwv[n][0], w1v = cwv[n][1], w2v = cwv[n][2], bv = cbv[n];
; #pragma unroll
;             for (int ai = 0; ai < 2; ++ai) {
;                 f32x4 hg = (f32x4){0.f, 0.f, 0.f, 0.f}, hv = hg;
;                 const int s = ai * 2 + wr;
;                 if (s > 0 && fr >= 14) {
;                     hg = *(const LAS f32x4*)(xch + (((s - 1) * 2 + (fr - 14)) * 256 + wc * 32 + fq * 8 + n * 4));
;                     hv = *(const LAS f32x4*)(xch + (((s - 1) * 2 + (fr - 14)) * 256 + 128 + wc * 32 + fq * 8 + n * 4));
;                 }
; #pragma unroll
;                 for (int m = 0; m < 4; ++m) {
;                     const int rl = ai * 128 + wr * 64 + m * 16 + fr;
;                     const f32x4 cg_ = acc[ai][0][m][n], cv_ = acc[ai][1][m][n];
;                     f32x4 p1g, p2g, p1v, p2v;
; #pragma unroll
;                     for (int j = 0; j < 4; ++j) {
;                         p1g[j] = ror1(fr == 15 ? hg[j] : cg_[j]); p2g[j] = ror2(fr >= 14 ? hg[j] : cg_[j]);
;                         p1v[j] = ror1(fr == 15 ? hv[j] : cv_[j]); p2v[j] = ror2(fr >= 14 ? hv[j] : cv_[j]);
	v_pk_mul_f32 v[134:135], v[134:135], v[126:127] op_sel_hi:[1,0]
	v_pk_mul_f32 v[24:25], v[24:25], v[126:127] op_sel_hi:[1,0]
	v_pk_mul_f32 v[26:27], v[26:27], v[126:127] op_sel_hi:[1,0]
	v_fmamk_f32 v126, v211, 0x3a800000, v223
	v_rsq_f32_e32 v126, v126
	s_nop 0
	v_pk_mul_f32 v[76:77], v[76:77], v[126:127] op_sel_hi:[1,0]
	v_pk_mul_f32 v[78:79], v[78:79], v[126:127] op_sel_hi:[1,0]
	v_pk_mul_f32 v[12:13], v[12:13], v[126:127] op_sel_hi:[1,0]
	v_pk_mul_f32 v[14:15], v[14:15], v[126:127] op_sel_hi:[1,0]
	v_pk_mul_f32 v[72:73], v[72:73], v[126:127] op_sel_hi:[1,0]
	v_pk_mul_f32 v[74:75], v[74:75], v[126:127] op_sel_hi:[1,0]
	v_pk_mul_f32 v[8:9], v[8:9], v[126:127] op_sel_hi:[1,0]
	v_pk_mul_f32 v[10:11], v[10:11], v[126:127] op_sel_hi:[1,0]
	v_fmamk_f32 v126, v212, 0x3a800000, v223
	v_rsq_f32_e32 v126, v126
	s_nop 0
	v_pk_mul_f32 v[68:69], v[68:69], v[126:127] op_sel_hi:[1,0]
	v_pk_mul_f32 v[70:71], v[70:71], v[126:127] op_sel_hi:[1,0]
	v_pk_mul_f32 v[4:5], v[4:5], v[126:127] op_sel_hi:[1,0]
	v_pk_mul_f32 v[6:7], v[6:7], v[126:127] op_sel_hi:[1,0]
	v_pk_mul_f32 v[64:65], v[64:65], v[126:127] op_sel_hi:[1,0]
	v_pk_mul_f32 v[66:67], v[66:67], v[126:127] op_sel_hi:[1,0]
	v_pk_mul_f32 v[0:1], v[0:1], v[126:127] op_sel_hi:[1,0]
	v_pk_mul_f32 v[2:3], v[2:3], v[126:127] op_sel_hi:[1,0]
	v_fmamk_f32 v126, v213, 0x3a800000, v223
	v_rsq_f32_e32 v126, v126
	s_nop 0
	v_pk_mul_f32 v[122:123], v[122:123], v[126:127] op_sel_hi:[1,0]
	v_pk_mul_f32 v[124:125], v[124:125], v[126:127] op_sel_hi:[1,0]
	v_pk_mul_f32 v[16:17], v[16:17], v[126:127] op_sel_hi:[1,0]
	v_pk_mul_f32 v[18:19], v[18:19], v[126:127] op_sel_hi:[1,0]
	v_pk_mul_f32 v[128:129], v[128:129], v[126:127] op_sel_hi:[1,0]
	v_pk_mul_f32 v[130:131], v[130:131], v[126:127] op_sel_hi:[1,0]
	v_pk_mul_f32 v[20:21], v[20:21], v[126:127] op_sel_hi:[1,0]
	v_pk_mul_f32 v[22:23], v[22:23], v[126:127] op_sel_hi:[1,0]
	s_and_saveexec_b64 s[20:21], s[50:51]
	s_cbranch_execz .Lmy_p5_xw
	ds_write_b128 v189, v[140:143]
	ds_write_b128 v189, v[114:117] offset:16
	ds_write_b128 v189, v[36:39] offset:32
	ds_write_b128 v189, v[32:35] offset:48
	ds_write_b128 v189, v[152:155] offset:64
	ds_write_b128 v189, v[148:151] offset:80
	ds_write_b128 v189, v[48:51] offset:96
	ds_write_b128 v189, v[44:47] offset:112
	ds_write_b128 v189, v[68:71] offset:4096
	ds_write_b128 v189, v[64:67] offset:4112
	ds_write_b128 v189, v[4:7] offset:4128
	ds_write_b128 v189, v[0:3] offset:4144
	ds_write_b128 v189, v[122:125] offset:4160
	ds_write_b128 v189, v[128:131] offset:4176
	ds_write_b128 v189, v[16:19] offset:4192
	ds_write_b128 v189, v[20:23] offset:4208
.Lmy_p5_xw:
	s_or_b64 exec, exec, s[20:21]
	s_waitcnt lgkmcnt(0)
	s_barrier
	v_mov_b64_e32 v[164:165], 0
	v_mov_b64_e32 v[166:167], 0
	v_mov_b64_e32 v[168:169], 0
	v_mov_b64_e32 v[170:171], 0
	v_mov_b64_e32 v[234:235], 0
	v_mov_b64_e32 v[236:237], 0
	v_mov_b64_e32 v[250:251], 0
	v_mov_b64_e32 v[252:253], 0
	s_and_saveexec_b64 s[20:21], s[80:81]
	s_cbranch_execz .Lmy_p5_1
	ds_read_b128 v[234:237], v188 offset:0
	ds_read_b128 v[250:253], v188 offset:16
	ds_read_b128 v[164:167], v188 offset:64
	ds_read_b128 v[168:171], v188 offset:80
.Lmy_p5_1:
	s_or_b64 exec, exec, s[20:21]
	s_waitcnt lgkmcnt(0)
	s_nop 4
	v_mov_b32_dpp v214, v152 row_ror:1 row_mask:0xf bank_mask:0xf
	v_mov_b32_dpp v215, v153 row_ror:1 row_mask:0xf bank_mask:0xf
	v_mov_b32_dpp v216, v154 row_ror:1 row_mask:0xf bank_mask:0xf
	v_mov_b32_dpp v217, v155 row_ror:1 row_mask:0xf bank_mask:0xf
	s_nop 1
	v_cndmask_b32_e64 v164, v214, v164, s[48:49]
	v_cndmask_b32_e64 v165, v215, v165, s[48:49]
	v_cndmask_b32_e64 v166, v216, v166, s[48:49]
	v_cndmask_b32_e64 v167, v217, v167, s[48:49]
	v_mov_b32_dpp v214, v148 row_ror:1 row_mask:0xf bank_mask:0xf
	v_mov_b32_dpp v215, v149 row_ror:1 row_mask:0xf bank_mask:0xf
	v_mov_b32_dpp v216, v150 row_ror:1 row_mask:0xf bank_mask:0xf
	v_mov_b32_dpp v217, v151 row_ror:1 row_mask:0xf bank_mask:0xf
	s_nop 1
	v_cndmask_b32_e64 v168, v214, v168, s[48:49]
	v_cndmask_b32_e64 v169, v215, v169, s[48:49]
	v_cndmask_b32_e64 v170, v216, v170, s[48:49]
	v_cndmask_b32_e64 v171, v217, v171, s[48:49]
	v_mov_b32_dpp v214, v140 row_ror:1 row_mask:0xf bank_mask:0xf
	v_mov_b32_dpp v215, v141 row_ror:1 row_mask:0xf bank_mask:0xf
	v_mov_b32_dpp v216, v142 row_ror:1 row_mask:0xf bank_mask:0xf
	v_mov_b32_dpp v217, v143 row_ror:1 row_mask:0xf bank_mask:0xf
	s_nop 1
	v_cndmask_b32_e64 v234, v214, v234, s[48:49]
	v_cndmask_b32_e64 v235, v215, v235, s[48:49]
	v_cndmask_b32_e64 v236, v216, v236, s[48:49]
	v_cndmask_b32_e64 v237, v217, v237, s[48:49]
	v_mov_b32_dpp v214, v114 row_ror:1 row_mask:0xf bank_mask:0xf
	v_mov_b32_dpp v215, v115 row_ror:1 row_mask:0xf bank_mask:0xf
	v_mov_b32_dpp v216, v116 row_ror:1 row_mask:0xf bank_mask:0xf
	v_mov_b32_dpp v217, v117 row_ror:1 row_mask:0xf bank_mask:0xf
	s_nop 1
	v_cndmask_b32_e64 v250, v214, v250, s[48:49]
	v_cndmask_b32_e64 v251, v215, v251, s[48:49]
	v_cndmask_b32_e64 v252, v216, v252, s[48:49]
	v_cndmask_b32_e64 v253, v217, v253, s[48:49]
	v_pk_fma_f32 v[206:207], v[102:103], v[234:235], v[98:99]
	v_pk_fma_f32 v[210:211], v[92:93], v[250:251], v[84:85]
	v_pk_fma_f32 v[208:209], v[104:105], v[236:237], v[100:101]
	v_pk_fma_f32 v[212:213], v[94:95], v[252:253], v[86:87]
	v_pk_fma_f32 v[206:207], v[106:107], v[164:165], v[206:207]
	v_pk_fma_f32 v[210:211], v[88:89], v[168:169], v[210:211]
	v_pk_fma_f32 v[208:209], v[108:109], v[166:167], v[208:209]
	v_pk_fma_f32 v[212:213], v[90:91], v[170:171], v[212:213]
	v_pk_fma_f32 v[206:207], v[110:111], v[160:161], v[206:207]
	v_pk_fma_f32 v[210:211], v[80:81], v[156:157], v[210:211]
	v_pk_fma_f32 v[208:209], v[112:113], v[162:163], v[208:209]
; __device__ __forceinline__ f32x2 gelu_pk(f32x2 v) {
;     const f32x2 av = __builtin_elementwise_abs(v), d = av * 0.2316418882f + 1.0f;
;     f32x2 t; t.x = __builtin_amdgcn_rcpf(d.x); t.y = __builtin_amdgcn_rcpf(d.y);
;     f32x2 q = t * 0.5307027145f + (-0.7265760135f); q = q * t + 0.7107068705f; q = q * t + (-0.142248368f); q = q * t + 0.127414796f; q = q * t;
;     const f32x2 s = (v * v) * (-0.72134752044f);
;     f32x2 e; e.x = __builtin_amdgcn_exp2f(s.x); e.y = __builtin_amdgcn_exp2f(s.y);
;     const f32x2 m = v * (q * e), r = v - m;
;     f32x2 o; o.x = v.x < 0.f ? m.x : r.x; o.y = v.y < 0.f ? m.y : r.y; return o;
; }
;     __device__ __forceinline__ void operator()(AccT& acc, const Unit& u, int wr, int wc, int fr, int fq) const {
;     ...
;                 for (int m = 0; m < 4; ++m) {
;                     const int rl = ai * 128 + wr * 64 + m * 16 + fr;
;                     const f32x4 cg_ = acc[ai][0][m][n], cv_ = acc[ai][1][m][n];
;                     f32x4 p1g, p2g, p1v, p2v;
; #pragma unroll
;                     for (int j = 0; j < 4; ++j) {
;                         p1g[j] = ror1(fr == 15 ? hg[j] : cg_[j]); p2g[j] = ror2(fr >= 14 ? hg[j] : cg_[j]);
;                         p1v[j] = ror1(fr == 15 ? hv[j] : cv_[j]); p2v[j] = ror2(fr >= 14 ? hv[j] : cv_[j]);
;                     }
;                     const f32x4 hcg = bg + w0g * p2g + w1g * p1g + w2g * cg_;
;                     const f32x4 hcv = bv + w0v * p2v + w1v * p1v + w2v * cv_;
;                     const f32x2 ga = gelu_pk((f32x2){hcg[0], hcg[1]}), gb2 = gelu_pk((f32x2){hcg[2], hcg[3]});
;                     u32x2 w; w.x = cvt_pk_bf16(ga.x * hcv[0], ga.y * hcv[1]); w.y = cvt_pk_bf16(gb2.x * hcv[2], gb2.y * hcv[3]);
;                     const int t = tstart + rl;
;                     if (n == 0) stash[ai][m] = w;
;                     else if (rl >= 2) *(u32x4*)(U + (size_t)(arow0 + rl) * FF + colg0) = (u32x4){stash[ai][m].x, stash[ai][m].y, w.x, w.y};
;                     if (rl < 2 || rl >= 254) { float* hp = halo + ((size_t)u.pm * 4 + (rl < 2 ? rl : rl - 252)) * FF2; *(f32x4*)(hp + colg) = cg_; *(f32x4*)(hp + colv) = cv_; }
;                     if (t >= SEQ - 2) { float* cp = conv_p + (size_t)(b * 2 + (t - (SEQ - 2))) * FF2; *(f32x4*)(cp + colg) = cg_; *(f32x4*)(cp + colv) = cv_; }
;                     hg = cg_; hv = cv_;
	v_pk_fma_f32 v[212:213], v[82:83], v[158:159], v[212:213]
	v_and_b32_e32 v214, 0x7fffffff, v206
	v_and_b32_e32 v215, 0x7fffffff, v207
	v_pk_mul_f32 v[218:219], v[206:207], v[206:207]
	v_pk_fma_f32 v[214:215], v[214:215], s[6:7], 1.0 op_sel_hi:[1,0,0]
	v_pk_mul_f32 v[218:219], v[218:219], s[36:37] op_sel_hi:[1,0]
	v_rcp_f32_e32 v214, v214
	v_rcp_f32_e32 v215, v215
	v_exp_f32_e32 v218, v218
	v_exp_f32_e32 v219, v219
	v_pk_fma_f32 v[216:217], v[214:215], s[24:25], v[186:187] op_sel_hi:[1,0,0]
	v_max_f32_e32 v220, 0, v206
	v_pk_fma_f32 v[216:217], v[214:215], v[216:217], s[28:29] op_sel_hi:[1,1,0]
	v_max_f32_e32 v221, 0, v207
	v_pk_fma_f32 v[216:217], v[214:215], v[216:217], s[30:31] op_sel_hi:[1,1,0]
	s_nop 0
	v_pk_fma_f32 v[216:217], v[214:215], v[216:217], s[34:35] op_sel_hi:[1,1,0]
	s_nop 0
	v_pk_mul_f32 v[216:217], v[214:215], v[216:217]
	s_nop 0
	v_pk_mul_f32 v[216:217], v[218:219], v[216:217]
	s_nop 0
	v_fma_f32 v206, -|v206|, v216, v220
	v_fma_f32 v207, -|v207|, v217, v221
	v_mul_f32_e32 v206, v210, v206
	v_mul_f32_e32 v207, v211, v207
	v_and_b32_e32 v214, 0x7fffffff, v208
	v_and_b32_e32 v215, 0x7fffffff, v209
	v_pk_mul_f32 v[218:219], v[208:209], v[208:209]
	v_pk_fma_f32 v[214:215], v[214:215], s[6:7], 1.0 op_sel_hi:[1,0,0]
	v_pk_mul_f32 v[218:219], v[218:219], s[36:37] op_sel_hi:[1,0]
	v_rcp_f32_e32 v214, v214
	v_rcp_f32_e32 v215, v215
	v_exp_f32_e32 v218, v218
	v_exp_f32_e32 v219, v219
	v_pk_fma_f32 v[216:217], v[214:215], s[24:25], v[186:187] op_sel_hi:[1,0,0]
	v_max_f32_e32 v220, 0, v208
	v_pk_fma_f32 v[216:217], v[214:215], v[216:217], s[28:29] op_sel_hi:[1,1,0]
	v_max_f32_e32 v221, 0, v209
	v_pk_fma_f32 v[216:217], v[214:215], v[216:217], s[30:31] op_sel_hi:[1,1,0]
	s_nop 0
	v_pk_fma_f32 v[216:217], v[214:215], v[216:217], s[34:35] op_sel_hi:[1,1,0]
	s_nop 0
	v_pk_mul_f32 v[216:217], v[214:215], v[216:217]
	s_nop 0
	v_pk_mul_f32 v[216:217], v[218:219], v[216:217]
	s_nop 0
	v_fma_f32 v208, -|v208|, v216, v220
	v_fma_f32 v209, -|v209|, v217, v221
	v_mul_f32_e32 v208, v212, v208
	v_mul_f32_e32 v209, v213, v209
	v_cvt_pk_bf16_f32 v190, v206, v207
	v_cvt_pk_bf16_f32 v191, v208, v209
	s_and_saveexec_b64 s[22:23], s[74:75]
	s_cbranch_execz .Lmy_p5_2
	s_lshr_b32 s18, s16, 6
	s_add_i32 s18, s18, 0
	s_mul_i32 s18, s18, 0x5800
	s_mov_b32 s19, 0
	v_lshlrev_b64 v[214:215], 2, v[182:183]
	v_lshl_add_u64 v[214:215], s[18:19], 0, v[214:215]
	v_lshl_add_u64 v[214:215], s[92:93], 0, v[214:215]
	global_store_dwordx4 v[214:215], v[160:163], off
	v_lshl_add_u64 v[216:217], v[214:215], 0, s[52:53]
	global_store_dwordx4 v[216:217], v[156:159], off offset:3072
.Lmy_p5_2:
	s_or_b64 exec, exec, s[22:23]
	v_pk_fma_f32 v[206:207], v[102:103], v[164:165], v[98:99]
	v_pk_fma_f32 v[210:211], v[92:93], v[168:169], v[84:85]
	v_pk_fma_f32 v[208:209], v[104:105], v[166:167], v[100:101]
	v_pk_fma_f32 v[212:213], v[94:95], v[170:171], v[86:87]
	v_pk_fma_f32 v[206:207], v[106:107], v[160:161], v[206:207]
	v_pk_fma_f32 v[210:211], v[88:89], v[156:157], v[210:211]
	v_pk_fma_f32 v[208:209], v[108:109], v[162:163], v[208:209]
	v_pk_fma_f32 v[212:213], v[90:91], v[158:159], v[212:213]
	v_pk_fma_f32 v[206:207], v[110:111], v[144:145], v[206:207]
	v_pk_fma_f32 v[210:211], v[80:81], v[118:119], v[210:211]
	v_pk_fma_f32 v[208:209], v[112:113], v[146:147], v[208:209]
	v_pk_fma_f32 v[212:213], v[82:83], v[120:121], v[212:213]
	v_and_b32_e32 v214, 0x7fffffff, v206
	v_and_b32_e32 v215, 0x7fffffff, v207
	v_pk_mul_f32 v[218:219], v[206:207], v[206:207]
	v_pk_fma_f32 v[214:215], v[214:215], s[6:7], 1.0 op_sel_hi:[1,0,0]
	v_pk_mul_f32 v[218:219], v[218:219], s[36:37] op_sel_hi:[1,0]
	v_rcp_f32_e32 v214, v214
	v_rcp_f32_e32 v215, v215
	v_exp_f32_e32 v218, v218
	v_exp_f32_e32 v219, v219
	v_pk_fma_f32 v[216:217], v[214:215], s[24:25], v[186:187] op_sel_hi:[1,0,0]
	v_max_f32_e32 v220, 0, v206
	v_pk_fma_f32 v[216:217], v[214:215], v[216:217], s[28:29] op_sel_hi:[1,1,0]
	v_max_f32_e32 v221, 0, v207
	v_pk_fma_f32 v[216:217], v[214:215], v[216:217], s[30:31] op_sel_hi:[1,1,0]
	s_nop 0
	v_pk_fma_f32 v[216:217], v[214:215], v[216:217], s[34:35] op_sel_hi:[1,1,0]
	s_nop 0
	v_pk_mul_f32 v[216:217], v[214:215], v[216:217]
	s_nop 0
	v_pk_mul_f32 v[216:217], v[218:219], v[216:217]
	s_nop 0
	v_fma_f32 v206, -|v206|, v216, v220
	v_fma_f32 v207, -|v207|, v217, v221
	v_mul_f32_e32 v206, v210, v206
	v_mul_f32_e32 v207, v211, v207
	v_and_b32_e32 v214, 0x7fffffff, v208
	v_and_b32_e32 v215, 0x7fffffff, v209
	v_pk_mul_f32 v[218:219], v[208:209], v[208:209]
	v_pk_fma_f32 v[214:215], v[214:215], s[6:7], 1.0 op_sel_hi:[1,0,0]
	v_pk_mul_f32 v[218:219], v[218:219], s[36:37] op_sel_hi:[1,0]
	v_rcp_f32_e32 v214, v214
	v_rcp_f32_e32 v215, v215
	v_exp_f32_e32 v218, v218
	v_exp_f32_e32 v219, v219
	v_pk_fma_f32 v[216:217], v[214:215], s[24:25], v[186:187] op_sel_hi:[1,0,0]
	v_max_f32_e32 v220, 0, v208
	v_pk_fma_f32 v[216:217], v[214:215], v[216:217], s[28:29] op_sel_hi:[1,1,0]
	v_max_f32_e32 v221, 0, v209
	v_pk_fma_f32 v[216:217], v[214:215], v[216:217], s[30:31] op_sel_hi:[1,1,0]
	s_nop 0
	v_pk_fma_f32 v[216:217], v[214:215], v[216:217], s[34:35] op_sel_hi:[1,1,0]
	s_nop 0
	v_pk_mul_f32 v[216:217], v[214:215], v[216:217]
	s_nop 0
	v_pk_mul_f32 v[216:217], v[218:219], v[216:217]
	s_nop 0
	v_fma_f32 v208, -|v208|, v216, v220
	v_fma_f32 v209, -|v209|, v217, v221
	v_mul_f32_e32 v208, v212, v208
	v_mul_f32_e32 v209, v213, v209
	v_cvt_pk_bf16_f32 v238, v206, v207
	v_cvt_pk_bf16_f32 v239, v208, v209
	s_and_saveexec_b64 s[22:23], s[74:75]
	s_cbranch_execz .Lmy_p5_3
	s_lshr_b32 s18, s16, 6
	s_add_i32 s18, s18, 1
	s_mul_i32 s18, s18, 0x5800
	s_mov_b32 s19, 0
	v_lshlrev_b64 v[214:215], 2, v[182:183]
	v_lshl_add_u64 v[214:215], s[18:19], 0, v[214:215]
	v_lshl_add_u64 v[214:215], s[92:93], 0, v[214:215]
	global_store_dwordx4 v[214:215], v[144:147], off
	v_lshl_add_u64 v[216:217], v[214:215], 0, s[52:53]
	global_store_dwordx4 v[216:217], v[118:121], off offset:3072
; #define LAS __attribute__((address_space(3)))
; __device__ __forceinline__ f32x2 gelu_pk(f32x2 v) {
;     const f32x2 av = __builtin_elementwise_abs(v), d = av * 0.2316418882f + 1.0f;
;     __device__ __forceinline__ void operator()(AccT& acc, const Unit& u, int wr, int wc, int fr, int fq) const {
;     ...
;             for (int ai = 0; ai < 2; ++ai) {
;                 f32x4 hg = (f32x4){0.f, 0.f, 0.f, 0.f}, hv = hg;
;                 const int s = ai * 2 + wr;
;                 if (s > 0 && fr >= 14) {
;                     hg = *(const LAS f32x4*)(xch + (((s - 1) * 2 + (fr - 14)) * 256 + wc * 32 + fq * 8 + n * 4));
;                     hv = *(const LAS f32x4*)(xch + (((s - 1) * 2 + (fr - 14)) * 256 + 128 + wc * 32 + fq * 8 + n * 4));
;                 }
; #pragma unroll
;                 for (int m = 0; m < 4; ++m) {
;                     const int rl = ai * 128 + wr * 64 + m * 16 + fr;
;                     const f32x4 cg_ = acc[ai][0][m][n], cv_ = acc[ai][1][m][n];
;                     f32x4 p1g, p2g, p1v, p2v;
; #pragma unroll
;                     for (int j = 0; j < 4; ++j) {
;                         p1g[j] = ror1(fr == 15 ? hg[j] : cg_[j]); p2g[j] = ror2(fr >= 14 ? hg[j] : cg_[j]);
;                         p1v[j] = ror1(fr == 15 ? hv[j] : cv_[j]); p2v[j] = ror2(fr >= 14 ? hv[j] : cv_[j]);
;                     }
;                     const f32x4 hcg = bg + w0g * p2g + w1g * p1g + w2g * cg_;
;                     const f32x4 hcv = bv + w0v * p2v + w1v * p1v + w2v * cv_;
;                     const f32x2 ga = gelu_pk((f32x2){hcg[0], hcg[1]}), gb2 = gelu_pk((f32x2){hcg[2], hcg[3]});
;                     u32x2 w; w.x = cvt_pk_bf16(ga.x * hcv[0], ga.y * hcv[1]); w.y = cvt_pk_bf16(gb2.x * hcv[2], gb2.y * hcv[3]);
;                     const int t = tstart + rl;
;                     if (n == 0) stash[ai][m] = w;
;                     else if (rl >= 2) *(u32x4*)(U + (size_t)(arow0 + rl) * FF + colg0) = (u32x4){stash[ai][m].x, stash[ai][m].y, w.x, w.y};
;                     if (rl < 2 || rl >= 254) { float* hp = halo + ((size_t)u.pm * 4 + (rl < 2 ? rl : rl - 252)) * FF2; *(f32x4*)(hp + colg) = cg_; *(f32x4*)(hp + colv) = cv_; }
;                     if (t >= SEQ - 2) { float* cp = conv_p + (size_t)(b * 2 + (t - (SEQ - 2))) * FF2; *(f32x4*)(cp + colg) = cg_; *(f32x4*)(cp + colv) = cv_; }
;                     hg = cg_; hv = cv_;
.Lmy_p5_3:
	s_or_b64 exec, exec, s[22:23]
	v_pk_fma_f32 v[206:207], v[102:103], v[160:161], v[98:99]
	v_pk_fma_f32 v[210:211], v[92:93], v[156:157], v[84:85]
	v_pk_fma_f32 v[208:209], v[104:105], v[162:163], v[100:101]
	v_pk_fma_f32 v[212:213], v[94:95], v[158:159], v[86:87]
	v_pk_fma_f32 v[206:207], v[106:107], v[144:145], v[206:207]
	v_pk_fma_f32 v[210:211], v[88:89], v[118:119], v[210:211]
	v_pk_fma_f32 v[208:209], v[108:109], v[146:147], v[208:209]
	v_pk_fma_f32 v[212:213], v[90:91], v[120:121], v[212:213]
	v_pk_fma_f32 v[206:207], v[110:111], v[140:141], v[206:207]
	v_pk_fma_f32 v[210:211], v[80:81], v[114:115], v[210:211]
	v_pk_fma_f32 v[208:209], v[112:113], v[142:143], v[208:209]
	v_pk_fma_f32 v[212:213], v[82:83], v[116:117], v[212:213]
	v_and_b32_e32 v214, 0x7fffffff, v206
	v_and_b32_e32 v215, 0x7fffffff, v207
	v_pk_mul_f32 v[218:219], v[206:207], v[206:207]
	v_pk_fma_f32 v[214:215], v[214:215], s[6:7], 1.0 op_sel_hi:[1,0,0]
	v_pk_mul_f32 v[218:219], v[218:219], s[36:37] op_sel_hi:[1,0]
	v_rcp_f32_e32 v214, v214
	v_rcp_f32_e32 v215, v215
	v_exp_f32_e32 v218, v218
	v_exp_f32_e32 v219, v219
	v_pk_fma_f32 v[216:217], v[214:215], s[24:25], v[186:187] op_sel_hi:[1,0,0]
	v_max_f32_e32 v220, 0, v206
	v_pk_fma_f32 v[216:217], v[214:215], v[216:217], s[28:29] op_sel_hi:[1,1,0]
	v_max_f32_e32 v221, 0, v207
	v_pk_fma_f32 v[216:217], v[214:215], v[216:217], s[30:31] op_sel_hi:[1,1,0]
	s_nop 0
	v_pk_fma_f32 v[216:217], v[214:215], v[216:217], s[34:35] op_sel_hi:[1,1,0]
	s_nop 0
	v_pk_mul_f32 v[216:217], v[214:215], v[216:217]
	s_nop 0
	v_pk_mul_f32 v[216:217], v[218:219], v[216:217]
	s_nop 0
	v_fma_f32 v206, -|v206|, v216, v220
	v_fma_f32 v207, -|v207|, v217, v221
	v_mul_f32_e32 v206, v210, v206
	v_mul_f32_e32 v207, v211, v207
	v_and_b32_e32 v214, 0x7fffffff, v208
	v_and_b32_e32 v215, 0x7fffffff, v209
	v_pk_mul_f32 v[218:219], v[208:209], v[208:209]
	v_pk_fma_f32 v[214:215], v[214:215], s[6:7], 1.0 op_sel_hi:[1,0,0]
	v_pk_mul_f32 v[218:219], v[218:219], s[36:37] op_sel_hi:[1,0]
	v_rcp_f32_e32 v214, v214
	v_rcp_f32_e32 v215, v215
	v_exp_f32_e32 v218, v218
	v_exp_f32_e32 v219, v219
	v_pk_fma_f32 v[216:217], v[214:215], s[24:25], v[186:187] op_sel_hi:[1,0,0]
	v_max_f32_e32 v220, 0, v208
	v_pk_fma_f32 v[216:217], v[214:215], v[216:217], s[28:29] op_sel_hi:[1,1,0]
	v_max_f32_e32 v221, 0, v209
	v_pk_fma_f32 v[216:217], v[214:215], v[216:217], s[30:31] op_sel_hi:[1,1,0]
	s_nop 0
	v_pk_fma_f32 v[216:217], v[214:215], v[216:217], s[34:35] op_sel_hi:[1,1,0]
	s_nop 0
	v_pk_mul_f32 v[216:217], v[214:215], v[216:217]
	s_nop 0
	v_pk_mul_f32 v[216:217], v[218:219], v[216:217]
	s_nop 0
	v_fma_f32 v208, -|v208|, v216, v220
	v_fma_f32 v209, -|v209|, v217, v221
	v_mul_f32_e32 v208, v212, v208
	v_mul_f32_e32 v209, v213, v209
	v_cvt_pk_bf16_f32 v160, v206, v207
	v_cvt_pk_bf16_f32 v161, v208, v209
	v_pk_fma_f32 v[206:207], v[102:103], v[144:145], v[98:99]
	v_pk_fma_f32 v[210:211], v[92:93], v[118:119], v[84:85]
	v_pk_fma_f32 v[208:209], v[104:105], v[146:147], v[100:101]
	v_pk_fma_f32 v[212:213], v[94:95], v[120:121], v[86:87]
	v_pk_fma_f32 v[206:207], v[106:107], v[140:141], v[206:207]
	v_pk_fma_f32 v[210:211], v[88:89], v[114:115], v[210:211]
	v_pk_fma_f32 v[208:209], v[108:109], v[142:143], v[208:209]
	v_pk_fma_f32 v[212:213], v[90:91], v[116:117], v[212:213]
	v_pk_fma_f32 v[206:207], v[110:111], v[152:153], v[206:207]
	v_pk_fma_f32 v[210:211], v[80:81], v[148:149], v[210:211]
	v_pk_fma_f32 v[208:209], v[112:113], v[154:155], v[208:209]
	v_pk_fma_f32 v[212:213], v[82:83], v[150:151], v[212:213]
	v_and_b32_e32 v214, 0x7fffffff, v206
	v_and_b32_e32 v215, 0x7fffffff, v207
	v_pk_mul_f32 v[218:219], v[206:207], v[206:207]
	v_pk_fma_f32 v[214:215], v[214:215], s[6:7], 1.0 op_sel_hi:[1,0,0]
	v_pk_mul_f32 v[218:219], v[218:219], s[36:37] op_sel_hi:[1,0]
	v_rcp_f32_e32 v214, v214
	v_rcp_f32_e32 v215, v215
	v_exp_f32_e32 v218, v218
	v_exp_f32_e32 v219, v219
	v_pk_fma_f32 v[216:217], v[214:215], s[24:25], v[186:187] op_sel_hi:[1,0,0]
	v_max_f32_e32 v220, 0, v206
	v_pk_fma_f32 v[216:217], v[214:215], v[216:217], s[28:29] op_sel_hi:[1,1,0]
	v_max_f32_e32 v221, 0, v207
	v_pk_fma_f32 v[216:217], v[214:215], v[216:217], s[30:31] op_sel_hi:[1,1,0]
	s_nop 0
	v_pk_fma_f32 v[216:217], v[214:215], v[216:217], s[34:35] op_sel_hi:[1,1,0]
	s_nop 0
	v_pk_mul_f32 v[216:217], v[214:215], v[216:217]
	s_nop 0
	v_pk_mul_f32 v[216:217], v[218:219], v[216:217]
	s_nop 0
	v_fma_f32 v206, -|v206|, v216, v220
	v_fma_f32 v207, -|v207|, v217, v221
	v_mul_f32_e32 v206, v210, v206
	v_mul_f32_e32 v207, v211, v207
	v_and_b32_e32 v214, 0x7fffffff, v208
	v_and_b32_e32 v215, 0x7fffffff, v209
	v_pk_mul_f32 v[218:219], v[208:209], v[208:209]
	v_pk_fma_f32 v[214:215], v[214:215], s[6:7], 1.0 op_sel_hi:[1,0,0]
	v_pk_mul_f32 v[218:219], v[218:219], s[36:37] op_sel_hi:[1,0]
	v_rcp_f32_e32 v214, v214
	v_rcp_f32_e32 v215, v215
	v_exp_f32_e32 v218, v218
	v_exp_f32_e32 v219, v219
	v_pk_fma_f32 v[216:217], v[214:215], s[24:25], v[186:187] op_sel_hi:[1,0,0]
	v_max_f32_e32 v220, 0, v208
	v_pk_fma_f32 v[216:217], v[214:215], v[216:217], s[28:29] op_sel_hi:[1,1,0]
	v_max_f32_e32 v221, 0, v209
	v_pk_fma_f32 v[216:217], v[214:215], v[216:217], s[30:31] op_sel_hi:[1,1,0]
	s_nop 0
	v_pk_fma_f32 v[216:217], v[214:215], v[216:217], s[34:35] op_sel_hi:[1,1,0]
	s_nop 0
	v_pk_mul_f32 v[216:217], v[214:215], v[216:217]
	s_nop 0
	v_pk_mul_f32 v[216:217], v[218:219], v[216:217]
	s_nop 0
	v_fma_f32 v208, -|v208|, v216, v220
	v_fma_f32 v209, -|v209|, v217, v221
	v_mul_f32_e32 v208, v212, v208
	v_mul_f32_e32 v209, v213, v209
	v_cvt_pk_bf16_f32 v144, v206, v207
	v_cvt_pk_bf16_f32 v145, v208, v209
	v_mov_b64_e32 v[164:165], 0
	v_mov_b64_e32 v[166:167], 0
	v_mov_b64_e32 v[168:169], 0
	v_mov_b64_e32 v[170:171], 0
	v_mov_b64_e32 v[234:235], 0
	v_mov_b64_e32 v[236:237], 0
	v_mov_b64_e32 v[250:251], 0
	v_mov_b64_e32 v[252:253], 0
	s_and_saveexec_b64 s[20:21], s[48:49]
	s_cbranch_execz .Lmy_p5_4
	ds_read_b128 v[234:237], v188 offset:4096
	ds_read_b128 v[250:253], v188 offset:4112
	ds_read_b128 v[164:167], v188 offset:4160
	ds_read_b128 v[168:171], v188 offset:4176
; #define LAS __attribute__((address_space(3)))
; __device__ __forceinline__ f32x2 gelu_pk(f32x2 v) {
;     const f32x2 av = __builtin_elementwise_abs(v), d = av * 0.2316418882f + 1.0f;
;     __device__ __forceinline__ void operator()(AccT& acc, const Unit& u, int wr, int wc, int fr, int fq) const {
;     ...
;             for (int ai = 0; ai < 2; ++ai) {
;                 f32x4 hg = (f32x4){0.f, 0.f, 0.f, 0.f}, hv = hg;
;                 const int s = ai * 2 + wr;
;                 if (s > 0 && fr >= 14) {
;                     hg = *(const LAS f32x4*)(xch + (((s - 1) * 2 + (fr - 14)) * 256 + wc * 32 + fq * 8 + n * 4));
;                     hv = *(const LAS f32x4*)(xch + (((s - 1) * 2 + (fr - 14)) * 256 + 128 + wc * 32 + fq * 8 + n * 4));
;                 }
; #pragma unroll
;                 for (int m = 0; m < 4; ++m) {
;                     const int rl = ai * 128 + wr * 64 + m * 16 + fr;
;                     const f32x4 cg_ = acc[ai][0][m][n], cv_ = acc[ai][1][m][n];
;                     f32x4 p1g, p2g, p1v, p2v;
; #pragma unroll
;                     for (int j = 0; j < 4; ++j) {
;                         p1g[j] = ror1(fr == 15 ? hg[j] : cg_[j]); p2g[j] = ror2(fr >= 14 ? hg[j] : cg_[j]);
;                         p1v[j] = ror1(fr == 15 ? hv[j] : cv_[j]); p2v[j] = ror2(fr >= 14 ? hv[j] : cv_[j]);
;                     }
;                     const f32x4 hcg = bg + w0g * p2g + w1g * p1g + w2g * cg_;
;                     const f32x4 hcv = bv + w0v * p2v + w1v * p1v + w2v * cv_;
;                     const f32x2 ga = gelu_pk((f32x2){hcg[0], hcg[1]}), gb2 = gelu_pk((f32x2){hcg[2], hcg[3]});
;                     u32x2 w; w.x = cvt_pk_bf16(ga.x * hcv[0], ga.y * hcv[1]); w.y = cvt_pk_bf16(gb2.x * hcv[2], gb2.y * hcv[3]);
;                     const int t = tstart + rl;
;                     if (n == 0) stash[ai][m] = w;
;                     else if (rl >= 2) *(u32x4*)(U + (size_t)(arow0 + rl) * FF + colg0) = (u32x4){stash[ai][m].x, stash[ai][m].y, w.x, w.y};
;                     if (rl < 2 || rl >= 254) { float* hp = halo + ((size_t)u.pm * 4 + (rl < 2 ? rl : rl - 252)) * FF2; *(f32x4*)(hp + colg) = cg_; *(f32x4*)(hp + colv) = cv_; }
;                     if (t >= SEQ - 2) { float* cp = conv_p + (size_t)(b * 2 + (t - (SEQ - 2))) * FF2; *(f32x4*)(cp + colg) = cg_; *(f32x4*)(cp + colv) = cv_; }
;                     hg = cg_; hv = cv_;
.Lmy_p5_4:
	s_or_b64 exec, exec, s[20:21]
	s_waitcnt lgkmcnt(0)
	s_nop 4
	v_mov_b32_dpp v214, v122 row_ror:1 row_mask:0xf bank_mask:0xf
	v_mov_b32_dpp v215, v123 row_ror:1 row_mask:0xf bank_mask:0xf
	v_mov_b32_dpp v216, v124 row_ror:1 row_mask:0xf bank_mask:0xf
	v_mov_b32_dpp v217, v125 row_ror:1 row_mask:0xf bank_mask:0xf
	s_nop 1
	v_cndmask_b32_e64 v164, v214, v164, s[48:49]
	v_cndmask_b32_e64 v165, v215, v165, s[48:49]
	v_cndmask_b32_e64 v166, v216, v166, s[48:49]
	v_cndmask_b32_e64 v167, v217, v167, s[48:49]
	v_mov_b32_dpp v214, v128 row_ror:1 row_mask:0xf bank_mask:0xf
	v_mov_b32_dpp v215, v129 row_ror:1 row_mask:0xf bank_mask:0xf
	v_mov_b32_dpp v216, v130 row_ror:1 row_mask:0xf bank_mask:0xf
	v_mov_b32_dpp v217, v131 row_ror:1 row_mask:0xf bank_mask:0xf
	s_nop 1
	v_cndmask_b32_e64 v168, v214, v168, s[48:49]
	v_cndmask_b32_e64 v169, v215, v169, s[48:49]
	v_cndmask_b32_e64 v170, v216, v170, s[48:49]
	v_cndmask_b32_e64 v171, v217, v171, s[48:49]
	v_mov_b32_dpp v214, v68 row_ror:1 row_mask:0xf bank_mask:0xf
	v_mov_b32_dpp v215, v69 row_ror:1 row_mask:0xf bank_mask:0xf
	v_mov_b32_dpp v216, v70 row_ror:1 row_mask:0xf bank_mask:0xf
	v_mov_b32_dpp v217, v71 row_ror:1 row_mask:0xf bank_mask:0xf
	s_nop 1
	v_cndmask_b32_e64 v234, v214, v234, s[48:49]
	v_cndmask_b32_e64 v235, v215, v235, s[48:49]
	v_cndmask_b32_e64 v236, v216, v236, s[48:49]
	v_cndmask_b32_e64 v237, v217, v237, s[48:49]
	v_mov_b32_dpp v214, v64 row_ror:1 row_mask:0xf bank_mask:0xf
	v_mov_b32_dpp v215, v65 row_ror:1 row_mask:0xf bank_mask:0xf
	v_mov_b32_dpp v216, v66 row_ror:1 row_mask:0xf bank_mask:0xf
	v_mov_b32_dpp v217, v67 row_ror:1 row_mask:0xf bank_mask:0xf
	s_nop 1
	v_cndmask_b32_e64 v250, v214, v250, s[48:49]
	v_cndmask_b32_e64 v251, v215, v251, s[48:49]
	v_cndmask_b32_e64 v252, v216, v252, s[48:49]
	v_cndmask_b32_e64 v253, v217, v253, s[48:49]
	v_pk_fma_f32 v[206:207], v[102:103], v[234:235], v[98:99]
	v_pk_fma_f32 v[210:211], v[92:93], v[250:251], v[84:85]
	v_pk_fma_f32 v[208:209], v[104:105], v[236:237], v[100:101]
	v_pk_fma_f32 v[212:213], v[94:95], v[252:253], v[86:87]
	v_pk_fma_f32 v[206:207], v[106:107], v[164:165], v[206:207]
	v_pk_fma_f32 v[210:211], v[88:89], v[168:169], v[210:211]
	v_pk_fma_f32 v[208:209], v[108:109], v[166:167], v[208:209]
	v_pk_fma_f32 v[212:213], v[90:91], v[170:171], v[212:213]
	v_pk_fma_f32 v[206:207], v[110:111], v[136:137], v[206:207]
	v_pk_fma_f32 v[210:211], v[80:81], v[132:133], v[210:211]
	v_pk_fma_f32 v[208:209], v[112:113], v[138:139], v[208:209]
	v_pk_fma_f32 v[212:213], v[82:83], v[134:135], v[212:213]
	v_and_b32_e32 v214, 0x7fffffff, v206
	v_and_b32_e32 v215, 0x7fffffff, v207
	v_pk_mul_f32 v[218:219], v[206:207], v[206:207]
	v_pk_fma_f32 v[214:215], v[214:215], s[6:7], 1.0 op_sel_hi:[1,0,0]
	v_pk_mul_f32 v[218:219], v[218:219], s[36:37] op_sel_hi:[1,0]
	v_rcp_f32_e32 v214, v214
	v_rcp_f32_e32 v215, v215
	v_exp_f32_e32 v218, v218
	v_exp_f32_e32 v219, v219
	v_pk_fma_f32 v[216:217], v[214:215], s[24:25], v[186:187] op_sel_hi:[1,0,0]
	v_max_f32_e32 v220, 0, v206
	v_pk_fma_f32 v[216:217], v[214:215], v[216:217], s[28:29] op_sel_hi:[1,1,0]
	v_max_f32_e32 v221, 0, v207
	v_pk_fma_f32 v[216:217], v[214:215], v[216:217], s[30:31] op_sel_hi:[1,1,0]
	s_nop 0
	v_pk_fma_f32 v[216:217], v[214:215], v[216:217], s[34:35] op_sel_hi:[1,1,0]
	s_nop 0
	v_pk_mul_f32 v[216:217], v[214:215], v[216:217]
	s_nop 0
	v_pk_mul_f32 v[216:217], v[218:219], v[216:217]
	s_nop 0
	v_fma_f32 v206, -|v206|, v216, v220
	v_fma_f32 v207, -|v207|, v217, v221
	v_mul_f32_e32 v206, v210, v206
	v_mul_f32_e32 v207, v211, v207
	v_and_b32_e32 v214, 0x7fffffff, v208
	v_and_b32_e32 v215, 0x7fffffff, v209
	v_pk_mul_f32 v[218:219], v[208:209], v[208:209]
	v_pk_fma_f32 v[214:215], v[214:215], s[6:7], 1.0 op_sel_hi:[1,0,0]
	v_pk_mul_f32 v[218:219], v[218:219], s[36:37] op_sel_hi:[1,0]
	v_rcp_f32_e32 v214, v214
	v_rcp_f32_e32 v215, v215
	v_exp_f32_e32 v218, v218
	v_exp_f32_e32 v219, v219
	v_pk_fma_f32 v[216:217], v[214:215], s[24:25], v[186:187] op_sel_hi:[1,0,0]
	v_max_f32_e32 v220, 0, v208
	v_pk_fma_f32 v[216:217], v[214:215], v[216:217], s[28:29] op_sel_hi:[1,1,0]
	v_max_f32_e32 v221, 0, v209
	v_pk_fma_f32 v[216:217], v[214:215], v[216:217], s[30:31] op_sel_hi:[1,1,0]
	s_nop 0
	v_pk_fma_f32 v[216:217], v[214:215], v[216:217], s[34:35] op_sel_hi:[1,1,0]
	s_nop 0
	v_pk_mul_f32 v[216:217], v[214:215], v[216:217]
	s_nop 0
	v_pk_mul_f32 v[216:217], v[218:219], v[216:217]
	s_nop 0
	v_fma_f32 v208, -|v208|, v216, v220
	v_fma_f32 v209, -|v209|, v217, v221
	v_mul_f32_e32 v208, v212, v208
	v_mul_f32_e32 v209, v213, v209
	v_cvt_pk_bf16_f32 v156, v206, v207
	v_cvt_pk_bf16_f32 v157, v208, v209
	v_pk_fma_f32 v[206:207], v[102:103], v[164:165], v[98:99]
	v_pk_fma_f32 v[210:211], v[92:93], v[168:169], v[84:85]
	v_pk_fma_f32 v[208:209], v[104:105], v[166:167], v[100:101]
	v_pk_fma_f32 v[212:213], v[94:95], v[170:171], v[86:87]
	v_pk_fma_f32 v[206:207], v[106:107], v[136:137], v[206:207]
	v_pk_fma_f32 v[210:211], v[88:89], v[132:133], v[210:211]
	v_pk_fma_f32 v[208:209], v[108:109], v[138:139], v[208:209]
	v_pk_fma_f32 v[212:213], v[90:91], v[134:135], v[212:213]
	v_pk_fma_f32 v[206:207], v[110:111], v[76:77], v[206:207]
	v_pk_fma_f32 v[210:211], v[80:81], v[72:73], v[210:211]
	v_pk_fma_f32 v[208:209], v[112:113], v[78:79], v[208:209]
	v_pk_fma_f32 v[212:213], v[82:83], v[74:75], v[212:213]
	v_and_b32_e32 v214, 0x7fffffff, v206
	v_and_b32_e32 v215, 0x7fffffff, v207
	v_pk_mul_f32 v[218:219], v[206:207], v[206:207]
	v_pk_fma_f32 v[214:215], v[214:215], s[6:7], 1.0 op_sel_hi:[1,0,0]
	v_pk_mul_f32 v[218:219], v[218:219], s[36:37] op_sel_hi:[1,0]
	v_rcp_f32_e32 v214, v214
	v_rcp_f32_e32 v215, v215
; __device__ __forceinline__ f32x2 gelu_pk(f32x2 v) {
;     const f32x2 av = __builtin_elementwise_abs(v), d = av * 0.2316418882f + 1.0f;
;     f32x2 t; t.x = __builtin_amdgcn_rcpf(d.x); t.y = __builtin_amdgcn_rcpf(d.y);
;     f32x2 q = t * 0.5307027145f + (-0.7265760135f); q = q * t + 0.7107068705f; q = q * t + (-0.142248368f); q = q * t + 0.127414796f; q = q * t;
;     const f32x2 s = (v * v) * (-0.72134752044f);
;     f32x2 e; e.x = __builtin_amdgcn_exp2f(s.x); e.y = __builtin_amdgcn_exp2f(s.y);
;     const f32x2 m = v * (q * e), r = v - m;
;     f32x2 o; o.x = v.x < 0.f ? m.x : r.x; o.y = v.y < 0.f ? m.y : r.y; return o;
; }
;     __device__ __forceinline__ void operator()(AccT& acc, const Unit& u, int wr, int wc, int fr, int fq) const {
;     ...
;                 for (int m = 0; m < 4; ++m) {
;                     const int rl = ai * 128 + wr * 64 + m * 16 + fr;
;                     const f32x4 cg_ = acc[ai][0][m][n], cv_ = acc[ai][1][m][n];
;                     f32x4 p1g, p2g, p1v, p2v;
; #pragma unroll
;                     for (int j = 0; j < 4; ++j) {
;                         p1g[j] = ror1(fr == 15 ? hg[j] : cg_[j]); p2g[j] = ror2(fr >= 14 ? hg[j] : cg_[j]);
;                         p1v[j] = ror1(fr == 15 ? hv[j] : cv_[j]); p2v[j] = ror2(fr >= 14 ? hv[j] : cv_[j]);
;                     }
;                     const f32x4 hcg = bg + w0g * p2g + w1g * p1g + w2g * cg_;
;                     const f32x4 hcv = bv + w0v * p2v + w1v * p1v + w2v * cv_;
;                     const f32x2 ga = gelu_pk((f32x2){hcg[0], hcg[1]}), gb2 = gelu_pk((f32x2){hcg[2], hcg[3]});
;                     u32x2 w; w.x = cvt_pk_bf16(ga.x * hcv[0], ga.y * hcv[1]); w.y = cvt_pk_bf16(gb2.x * hcv[2], gb2.y * hcv[3]);
;                     const int t = tstart + rl;
;                     if (n == 0) stash[ai][m] = w;
;                     else if (rl >= 2) *(u32x4*)(U + (size_t)(arow0 + rl) * FF + colg0) = (u32x4){stash[ai][m].x, stash[ai][m].y, w.x, w.y};
;                     if (rl < 2 || rl >= 254) { float* hp = halo + ((size_t)u.pm * 4 + (rl < 2 ? rl : rl - 252)) * FF2; *(f32x4*)(hp + colg) = cg_; *(f32x4*)(hp + colv) = cv_; }
;                     if (t >= SEQ - 2) { float* cp = conv_p + (size_t)(b * 2 + (t - (SEQ - 2))) * FF2; *(f32x4*)(cp + colg) = cg_; *(f32x4*)(cp + colv) = cv_; }
;                     hg = cg_; hv = cv_;
	v_exp_f32_e32 v218, v218
	v_exp_f32_e32 v219, v219
	v_pk_fma_f32 v[216:217], v[214:215], s[24:25], v[186:187] op_sel_hi:[1,0,0]
	v_max_f32_e32 v220, 0, v206
	v_pk_fma_f32 v[216:217], v[214:215], v[216:217], s[28:29] op_sel_hi:[1,1,0]
	v_max_f32_e32 v221, 0, v207
	v_pk_fma_f32 v[216:217], v[214:215], v[216:217], s[30:31] op_sel_hi:[1,1,0]
	s_nop 0
	v_pk_fma_f32 v[216:217], v[214:215], v[216:217], s[34:35] op_sel_hi:[1,1,0]
	s_nop 0
	v_pk_mul_f32 v[216:217], v[214:215], v[216:217]
	s_nop 0
	v_pk_mul_f32 v[216:217], v[218:219], v[216:217]
	s_nop 0
	v_fma_f32 v206, -|v206|, v216, v220
	v_fma_f32 v207, -|v207|, v217, v221
	v_mul_f32_e32 v206, v210, v206
	v_mul_f32_e32 v207, v211, v207
	v_and_b32_e32 v214, 0x7fffffff, v208
	v_and_b32_e32 v215, 0x7fffffff, v209
	v_pk_mul_f32 v[218:219], v[208:209], v[208:209]
	v_pk_fma_f32 v[214:215], v[214:215], s[6:7], 1.0 op_sel_hi:[1,0,0]
	v_pk_mul_f32 v[218:219], v[218:219], s[36:37] op_sel_hi:[1,0]
	v_rcp_f32_e32 v214, v214
	v_rcp_f32_e32 v215, v215
	v_exp_f32_e32 v218, v218
	v_exp_f32_e32 v219, v219
	v_pk_fma_f32 v[216:217], v[214:215], s[24:25], v[186:187] op_sel_hi:[1,0,0]
	v_max_f32_e32 v220, 0, v208
	v_pk_fma_f32 v[216:217], v[214:215], v[216:217], s[28:29] op_sel_hi:[1,1,0]
	v_max_f32_e32 v221, 0, v209
	v_pk_fma_f32 v[216:217], v[214:215], v[216:217], s[30:31] op_sel_hi:[1,1,0]
	s_nop 0
	v_pk_fma_f32 v[216:217], v[214:215], v[216:217], s[34:35] op_sel_hi:[1,1,0]
	s_nop 0
	v_pk_mul_f32 v[216:217], v[214:215], v[216:217]
	s_nop 0
	v_pk_mul_f32 v[216:217], v[218:219], v[216:217]
	s_nop 0
	v_fma_f32 v208, -|v208|, v216, v220
	v_fma_f32 v209, -|v209|, v217, v221
	v_mul_f32_e32 v208, v212, v208
	v_mul_f32_e32 v209, v213, v209
	v_cvt_pk_bf16_f32 v118, v206, v207
	v_cvt_pk_bf16_f32 v119, v208, v209
	v_pk_fma_f32 v[206:207], v[102:103], v[136:137], v[98:99]
	v_pk_fma_f32 v[210:211], v[92:93], v[132:133], v[84:85]
	v_pk_fma_f32 v[208:209], v[104:105], v[138:139], v[100:101]
	v_pk_fma_f32 v[212:213], v[94:95], v[134:135], v[86:87]
	v_pk_fma_f32 v[206:207], v[106:107], v[76:77], v[206:207]
	v_pk_fma_f32 v[210:211], v[88:89], v[72:73], v[210:211]
	v_pk_fma_f32 v[208:209], v[108:109], v[78:79], v[208:209]
	v_pk_fma_f32 v[212:213], v[90:91], v[74:75], v[212:213]
	v_pk_fma_f32 v[206:207], v[110:111], v[68:69], v[206:207]
	v_pk_fma_f32 v[210:211], v[80:81], v[64:65], v[210:211]
	v_pk_fma_f32 v[208:209], v[112:113], v[70:71], v[208:209]
	v_pk_fma_f32 v[212:213], v[82:83], v[66:67], v[212:213]
	v_and_b32_e32 v214, 0x7fffffff, v206
	v_and_b32_e32 v215, 0x7fffffff, v207
	v_pk_mul_f32 v[218:219], v[206:207], v[206:207]
	v_pk_fma_f32 v[214:215], v[214:215], s[6:7], 1.0 op_sel_hi:[1,0,0]
	v_pk_mul_f32 v[218:219], v[218:219], s[36:37] op_sel_hi:[1,0]
	v_rcp_f32_e32 v214, v214
	v_rcp_f32_e32 v215, v215
	v_exp_f32_e32 v218, v218
	v_exp_f32_e32 v219, v219
	v_pk_fma_f32 v[216:217], v[214:215], s[24:25], v[186:187] op_sel_hi:[1,0,0]
	v_max_f32_e32 v220, 0, v206
	v_pk_fma_f32 v[216:217], v[214:215], v[216:217], s[28:29] op_sel_hi:[1,1,0]
	v_max_f32_e32 v221, 0, v207
	v_pk_fma_f32 v[216:217], v[214:215], v[216:217], s[30:31] op_sel_hi:[1,1,0]
	s_nop 0
	v_pk_fma_f32 v[216:217], v[214:215], v[216:217], s[34:35] op_sel_hi:[1,1,0]
	s_nop 0
	v_pk_mul_f32 v[216:217], v[214:215], v[216:217]
	s_nop 0
	v_pk_mul_f32 v[216:217], v[218:219], v[216:217]
	s_nop 0
	v_fma_f32 v206, -|v206|, v216, v220
	v_fma_f32 v207, -|v207|, v217, v221
	v_mul_f32_e32 v206, v210, v206
	v_mul_f32_e32 v207, v211, v207
	v_and_b32_e32 v214, 0x7fffffff, v208
	v_and_b32_e32 v215, 0x7fffffff, v209
	v_pk_mul_f32 v[218:219], v[208:209], v[208:209]
	v_pk_fma_f32 v[214:215], v[214:215], s[6:7], 1.0 op_sel_hi:[1,0,0]
	v_pk_mul_f32 v[218:219], v[218:219], s[36:37] op_sel_hi:[1,0]
	v_rcp_f32_e32 v214, v214
	v_rcp_f32_e32 v215, v215
	v_exp_f32_e32 v218, v218
	v_exp_f32_e32 v219, v219
	v_pk_fma_f32 v[216:217], v[214:215], s[24:25], v[186:187] op_sel_hi:[1,0,0]
	v_max_f32_e32 v220, 0, v208
	v_pk_fma_f32 v[216:217], v[214:215], v[216:217], s[28:29] op_sel_hi:[1,1,0]
	v_max_f32_e32 v221, 0, v209
	v_pk_fma_f32 v[216:217], v[214:215], v[216:217], s[30:31] op_sel_hi:[1,1,0]
	s_nop 0
	v_pk_fma_f32 v[216:217], v[214:215], v[216:217], s[34:35] op_sel_hi:[1,1,0]
	s_nop 0
	v_pk_mul_f32 v[216:217], v[214:215], v[216:217]
	s_nop 0
	v_pk_mul_f32 v[216:217], v[218:219], v[216:217]
	s_nop 0
	v_fma_f32 v208, -|v208|, v216, v220
	v_fma_f32 v209, -|v209|, v217, v221
	v_mul_f32_e32 v208, v212, v208
	v_mul_f32_e32 v209, v213, v209
	v_cvt_pk_bf16_f32 v140, v206, v207
	v_cvt_pk_bf16_f32 v141, v208, v209
	s_and_saveexec_b64 s[22:23], s[76:77]
	s_cbranch_execz .Lmy_p5_5
	s_lshr_b32 s18, s16, 6
	s_add_i32 s18, s18, 2
	s_mul_i32 s18, s18, 0x5800
	s_mov_b32 s19, 0
	v_lshlrev_b64 v[214:215], 2, v[182:183]
	v_lshl_add_u64 v[214:215], s[18:19], 0, v[214:215]
	v_lshl_add_u64 v[214:215], s[92:93], 0, v[214:215]
	global_store_dwordx4 v[214:215], v[68:71], off
	v_lshl_add_u64 v[216:217], v[214:215], 0, s[52:53]
	global_store_dwordx4 v[216:217], v[64:67], off offset:3072
	s_bfe_u32 s18, s16, 0x60008
	s_cmp_eq_u32 s18, 63
	s_cbranch_scc0 .Lmy_p5_5
	s_lshr_b32 s18, s16, 14
	s_lshl_b32 s18, s18, 1
	s_add_i32 s18, s18, 0
	s_mul_i32 s18, s18, 0x5800
	s_mov_b32 s19, 0
	v_lshlrev_b64 v[214:215], 2, v[182:183]
	v_lshl_add_u64 v[214:215], s[18:19], 0, v[214:215]
	v_lshl_add_u64 v[214:215], s[0:1], 0, v[214:215]
	global_store_dwordx4 v[214:215], v[68:71], off
	v_lshl_add_u64 v[216:217], v[214:215], 0, s[52:53]
	global_store_dwordx4 v[216:217], v[64:67], off offset:3072
; __device__ __forceinline__ f32x2 gelu_pk(f32x2 v) {
;     const f32x2 av = __builtin_elementwise_abs(v), d = av * 0.2316418882f + 1.0f;
;     f32x2 t; t.x = __builtin_amdgcn_rcpf(d.x); t.y = __builtin_amdgcn_rcpf(d.y);
;     f32x2 q = t * 0.5307027145f + (-0.7265760135f); q = q * t + 0.7107068705f; q = q * t + (-0.142248368f); q = q * t + 0.127414796f; q = q * t;
;     const f32x2 s = (v * v) * (-0.72134752044f);
;     f32x2 e; e.x = __builtin_amdgcn_exp2f(s.x); e.y = __builtin_amdgcn_exp2f(s.y);
;     const f32x2 m = v * (q * e), r = v - m;
;     f32x2 o; o.x = v.x < 0.f ? m.x : r.x; o.y = v.y < 0.f ? m.y : r.y; return o;
;     __device__ __forceinline__ void operator()(AccT& acc, const Unit& u, int wr, int wc, int fr, int fq) const {
;     ...
;                 for (int m = 0; m < 4; ++m) {
;                     const int rl = ai * 128 + wr * 64 + m * 16 + fr;
;                     const f32x4 cg_ = acc[ai][0][m][n], cv_ = acc[ai][1][m][n];
;                     f32x4 p1g, p2g, p1v, p2v;
; #pragma unroll
;                     for (int j = 0; j < 4; ++j) {
;                         p1g[j] = ror1(fr == 15 ? hg[j] : cg_[j]); p2g[j] = ror2(fr >= 14 ? hg[j] : cg_[j]);
;                         p1v[j] = ror1(fr == 15 ? hv[j] : cv_[j]); p2v[j] = ror2(fr >= 14 ? hv[j] : cv_[j]);
;                     }
;                     const f32x4 hcg = bg + w0g * p2g + w1g * p1g + w2g * cg_;
;                     const f32x4 hcv = bv + w0v * p2v + w1v * p1v + w2v * cv_;
;                     const f32x2 ga = gelu_pk((f32x2){hcg[0], hcg[1]}), gb2 = gelu_pk((f32x2){hcg[2], hcg[3]});
;                     u32x2 w; w.x = cvt_pk_bf16(ga.x * hcv[0], ga.y * hcv[1]); w.y = cvt_pk_bf16(gb2.x * hcv[2], gb2.y * hcv[3]);
;                     const int t = tstart + rl;
;                     if (n == 0) stash[ai][m] = w;
;                     else if (rl >= 2) *(u32x4*)(U + (size_t)(arow0 + rl) * FF + colg0) = (u32x4){stash[ai][m].x, stash[ai][m].y, w.x, w.y};
;                     if (rl < 2 || rl >= 254) { float* hp = halo + ((size_t)u.pm * 4 + (rl < 2 ? rl : rl - 252)) * FF2; *(f32x4*)(hp + colg) = cg_; *(f32x4*)(hp + colv) = cv_; }
;                     if (t >= SEQ - 2) { float* cp = conv_p + (size_t)(b * 2 + (t - (SEQ - 2))) * FF2; *(f32x4*)(cp + colg) = cg_; *(f32x4*)(cp + colv) = cv_; }
.Lmy_p5_5:
	s_or_b64 exec, exec, s[22:23]
	v_pk_fma_f32 v[206:207], v[102:103], v[76:77], v[98:99]
	v_pk_fma_f32 v[210:211], v[92:93], v[72:73], v[84:85]
	v_pk_fma_f32 v[208:209], v[104:105], v[78:79], v[100:101]
	v_pk_fma_f32 v[212:213], v[94:95], v[74:75], v[86:87]
	v_pk_fma_f32 v[206:207], v[106:107], v[68:69], v[206:207]
	v_pk_fma_f32 v[210:211], v[88:89], v[64:65], v[210:211]
	v_pk_fma_f32 v[208:209], v[108:109], v[70:71], v[208:209]
	v_pk_fma_f32 v[212:213], v[90:91], v[66:67], v[212:213]
	v_pk_fma_f32 v[206:207], v[110:111], v[122:123], v[206:207]
	v_pk_fma_f32 v[210:211], v[80:81], v[128:129], v[210:211]
	v_pk_fma_f32 v[208:209], v[112:113], v[124:125], v[208:209]
	v_pk_fma_f32 v[212:213], v[82:83], v[130:131], v[212:213]
	v_and_b32_e32 v214, 0x7fffffff, v206
	v_and_b32_e32 v215, 0x7fffffff, v207
	v_pk_mul_f32 v[218:219], v[206:207], v[206:207]
	v_pk_fma_f32 v[214:215], v[214:215], s[6:7], 1.0 op_sel_hi:[1,0,0]
	v_pk_mul_f32 v[218:219], v[218:219], s[36:37] op_sel_hi:[1,0]
	v_rcp_f32_e32 v214, v214
	v_rcp_f32_e32 v215, v215
	v_exp_f32_e32 v218, v218
	v_exp_f32_e32 v219, v219
	v_pk_fma_f32 v[216:217], v[214:215], s[24:25], v[186:187] op_sel_hi:[1,0,0]
	v_max_f32_e32 v220, 0, v206
	v_pk_fma_f32 v[216:217], v[214:215], v[216:217], s[28:29] op_sel_hi:[1,1,0]
	v_max_f32_e32 v221, 0, v207
	v_pk_fma_f32 v[216:217], v[214:215], v[216:217], s[30:31] op_sel_hi:[1,1,0]
	s_nop 0
	v_pk_fma_f32 v[216:217], v[214:215], v[216:217], s[34:35] op_sel_hi:[1,1,0]
	s_nop 0
	v_pk_mul_f32 v[216:217], v[214:215], v[216:217]
	s_nop 0
	v_pk_mul_f32 v[216:217], v[218:219], v[216:217]
	s_nop 0
	v_fma_f32 v206, -|v206|, v216, v220
	v_fma_f32 v207, -|v207|, v217, v221
	v_mul_f32_e32 v206, v210, v206
	v_mul_f32_e32 v207, v211, v207
	v_and_b32_e32 v214, 0x7fffffff, v208
	v_and_b32_e32 v215, 0x7fffffff, v209
	v_pk_mul_f32 v[218:219], v[208:209], v[208:209]
	v_pk_fma_f32 v[214:215], v[214:215], s[6:7], 1.0 op_sel_hi:[1,0,0]
	v_pk_mul_f32 v[218:219], v[218:219], s[36:37] op_sel_hi:[1,0]
	v_rcp_f32_e32 v214, v214
	v_rcp_f32_e32 v215, v215
	v_exp_f32_e32 v218, v218
	v_exp_f32_e32 v219, v219
	v_pk_fma_f32 v[216:217], v[214:215], s[24:25], v[186:187] op_sel_hi:[1,0,0]
	v_max_f32_e32 v220, 0, v208
	v_pk_fma_f32 v[216:217], v[214:215], v[216:217], s[28:29] op_sel_hi:[1,1,0]
	v_max_f32_e32 v221, 0, v209
	v_pk_fma_f32 v[216:217], v[214:215], v[216:217], s[30:31] op_sel_hi:[1,1,0]
	s_nop 0
	v_pk_fma_f32 v[216:217], v[214:215], v[216:217], s[34:35] op_sel_hi:[1,1,0]
	s_nop 0
	v_pk_mul_f32 v[216:217], v[214:215], v[216:217]
	s_nop 0
	v_pk_mul_f32 v[216:217], v[218:219], v[216:217]
	s_nop 0
	v_fma_f32 v208, -|v208|, v216, v220
	v_fma_f32 v209, -|v209|, v217, v221
	v_mul_f32_e32 v208, v212, v208
	v_mul_f32_e32 v209, v213, v209
	v_cvt_pk_bf16_f32 v152, v206, v207
	v_cvt_pk_bf16_f32 v153, v208, v209
	s_and_saveexec_b64 s[22:23], s[76:77]
	s_cbranch_execz .Lmy_p5_6
	s_lshr_b32 s18, s16, 6
	s_add_i32 s18, s18, 3
	s_mul_i32 s18, s18, 0x5800
	s_mov_b32 s19, 0
	v_lshlrev_b64 v[214:215], 2, v[182:183]
	v_lshl_add_u64 v[214:215], s[18:19], 0, v[214:215]
	v_lshl_add_u64 v[214:215], s[92:93], 0, v[214:215]
	global_store_dwordx4 v[214:215], v[122:125], off
	v_lshl_add_u64 v[216:217], v[214:215], 0, s[52:53]
	global_store_dwordx4 v[216:217], v[128:131], off offset:3072
	s_bfe_u32 s18, s16, 0x60008
	s_cmp_eq_u32 s18, 63
	s_cbranch_scc0 .Lmy_p5_6
	s_lshr_b32 s18, s16, 14
	s_lshl_b32 s18, s18, 1
	s_add_i32 s18, s18, 1
	s_mul_i32 s18, s18, 0x5800
	s_mov_b32 s19, 0
	v_lshlrev_b64 v[214:215], 2, v[182:183]
	v_lshl_add_u64 v[214:215], s[18:19], 0, v[214:215]
	v_lshl_add_u64 v[214:215], s[0:1], 0, v[214:215]
	global_store_dwordx4 v[214:215], v[122:125], off
	v_lshl_add_u64 v[216:217], v[214:215], 0, s[52:53]
	global_store_dwordx4 v[216:217], v[128:131], off offset:3072
.Lmy_p5_6:
	s_or_b64 exec, exec, s[22:23]
	v_lshlrev_b64 v[126:127], 2, v[182:183]
	v_lshl_add_u64 v[214:215], s[44:45], 0, v[126:127]
	global_load_dwordx4 v[98:101], v[214:215], off offset:16
	v_lshl_add_u64 v[214:215], v[214:215], 0, s[52:53]
	global_load_dwordx4 v[84:87], v[214:215], off offset:3088
	v_lshl_add_u64 v[214:215], s[40:41], 0, v[126:127]
	global_load_dwordx4 v[102:105], v[214:215], off offset:16
	v_lshl_add_u64 v[214:215], v[214:215], 0, s[52:53]
	global_load_dwordx4 v[92:95], v[214:215], off offset:3088
	v_lshl_add_u64 v[214:215], s[42:43], 0, v[126:127]
	global_load_dwordx4 v[106:109], v[214:215], off offset:16
	v_lshl_add_u64 v[214:215], v[214:215], 0, s[52:53]
	global_load_dwordx4 v[88:91], v[214:215], off offset:3088
	v_lshl_add_u64 v[214:215], s[94:95], 0, v[126:127]
	global_load_dwordx4 v[110:113], v[214:215], off offset:16
	v_lshl_add_u64 v[214:215], v[214:215], 0, s[52:53]
	global_load_dwordx4 v[80:83], v[214:215], off offset:3088
	s_waitcnt vmcnt(0)
	v_mov_b64_e32 v[164:165], 0
	v_mov_b64_e32 v[166:167], 0
	v_mov_b64_e32 v[168:169], 0
	v_mov_b64_e32 v[170:171], 0
	v_mov_b64_e32 v[234:235], 0
	v_mov_b64_e32 v[236:237], 0
	v_mov_b64_e32 v[250:251], 0
	v_mov_b64_e32 v[252:253], 0
	s_and_saveexec_b64 s[20:21], s[80:81]
	s_cbranch_execz .Lmy_p5_7
	ds_read_b128 v[234:237], v188 offset:32
	ds_read_b128 v[250:253], v188 offset:48
	ds_read_b128 v[164:167], v188 offset:96
	ds_read_b128 v[168:171], v188 offset:112
; __device__ __forceinline__ unsigned cvt_pk_bf16(float lo, float hi) { unsigned r; asm volatile("v_cvt_pk_bf16_f32 %0, %1, %2" : "=v"(r) : "v"(lo), "v"(hi)); return r; }
; __device__ __forceinline__ float ror1(float x) { return __builtin_bit_cast(float, __builtin_amdgcn_update_dpp(0, __builtin_bit_cast(int, x), 0x121, 0xf, 0xf, false)); }
; __device__ __forceinline__ f32x2 gelu_pk(f32x2 v) {
;     const f32x2 av = __builtin_elementwise_abs(v), d = av * 0.2316418882f + 1.0f;
;     f32x2 t; t.x = __builtin_amdgcn_rcpf(d.x); t.y = __builtin_amdgcn_rcpf(d.y);
;     f32x2 q = t * 0.5307027145f + (-0.7265760135f); q = q * t + 0.7107068705f; q = q * t + (-0.142248368f); q = q * t + 0.127414796f; q = q * t;
;     const f32x2 s = (v * v) * (-0.72134752044f);
;     f32x2 e; e.x = __builtin_amdgcn_exp2f(s.x); e.y = __builtin_amdgcn_exp2f(s.y);
;     const f32x2 m = v * (q * e), r = v - m;
;     f32x2 o; o.x = v.x < 0.f ? m.x : r.x; o.y = v.y < 0.f ? m.y : r.y; return o;
;     __device__ __forceinline__ void operator()(AccT& acc, const Unit& u, int wr, int wc, int fr, int fq) const {
;     ...
;                     const f32x4 cg_ = acc[ai][0][m][n], cv_ = acc[ai][1][m][n];
;                     f32x4 p1g, p2g, p1v, p2v;
; #pragma unroll
;                     for (int j = 0; j < 4; ++j) {
;                         p1g[j] = ror1(fr == 15 ? hg[j] : cg_[j]); p2g[j] = ror2(fr >= 14 ? hg[j] : cg_[j]);
;                         p1v[j] = ror1(fr == 15 ? hv[j] : cv_[j]); p2v[j] = ror2(fr >= 14 ? hv[j] : cv_[j]);
;                     }
;                     const f32x4 hcg = bg + w0g * p2g + w1g * p1g + w2g * cg_;
;                     const f32x4 hcv = bv + w0v * p2v + w1v * p1v + w2v * cv_;
;                     const f32x2 ga = gelu_pk((f32x2){hcg[0], hcg[1]}), gb2 = gelu_pk((f32x2){hcg[2], hcg[3]});
;                     u32x2 w; w.x = cvt_pk_bf16(ga.x * hcv[0], ga.y * hcv[1]); w.y = cvt_pk_bf16(gb2.x * hcv[2], gb2.y * hcv[3]);
;                     const int t = tstart + rl;
;                     if (n == 0) stash[ai][m] = w;
;                     else if (rl >= 2) *(u32x4*)(U + (size_t)(arow0 + rl) * FF + colg0) = (u32x4){stash[ai][m].x, stash[ai][m].y, w.x, w.y};
;                     if (rl < 2 || rl >= 254) { float* hp = halo + ((size_t)u.pm * 4 + (rl < 2 ? rl : rl - 252)) * FF2; *(f32x4*)(hp + colg) = cg_; *(f32x4*)(hp + colv) = cv_; }
.Lmy_p5_7:
	s_or_b64 exec, exec, s[20:21]
	s_waitcnt lgkmcnt(0)
	s_nop 4
	v_mov_b32_dpp v214, v48 row_ror:1 row_mask:0xf bank_mask:0xf
	v_mov_b32_dpp v215, v49 row_ror:1 row_mask:0xf bank_mask:0xf
	v_mov_b32_dpp v216, v50 row_ror:1 row_mask:0xf bank_mask:0xf
	v_mov_b32_dpp v217, v51 row_ror:1 row_mask:0xf bank_mask:0xf
	s_nop 1
	v_cndmask_b32_e64 v164, v214, v164, s[48:49]
	v_cndmask_b32_e64 v165, v215, v165, s[48:49]
	v_cndmask_b32_e64 v166, v216, v166, s[48:49]
	v_cndmask_b32_e64 v167, v217, v167, s[48:49]
	v_mov_b32_dpp v214, v44 row_ror:1 row_mask:0xf bank_mask:0xf
	v_mov_b32_dpp v215, v45 row_ror:1 row_mask:0xf bank_mask:0xf
	v_mov_b32_dpp v216, v46 row_ror:1 row_mask:0xf bank_mask:0xf
	v_mov_b32_dpp v217, v47 row_ror:1 row_mask:0xf bank_mask:0xf
	s_nop 1
	v_cndmask_b32_e64 v168, v214, v168, s[48:49]
	v_cndmask_b32_e64 v169, v215, v169, s[48:49]
	v_cndmask_b32_e64 v170, v216, v170, s[48:49]
	v_cndmask_b32_e64 v171, v217, v171, s[48:49]
	v_mov_b32_dpp v214, v36 row_ror:1 row_mask:0xf bank_mask:0xf
	v_mov_b32_dpp v215, v37 row_ror:1 row_mask:0xf bank_mask:0xf
	v_mov_b32_dpp v216, v38 row_ror:1 row_mask:0xf bank_mask:0xf
	v_mov_b32_dpp v217, v39 row_ror:1 row_mask:0xf bank_mask:0xf
	s_nop 1
	v_cndmask_b32_e64 v234, v214, v234, s[48:49]
	v_cndmask_b32_e64 v235, v215, v235, s[48:49]
	v_cndmask_b32_e64 v236, v216, v236, s[48:49]
	v_cndmask_b32_e64 v237, v217, v237, s[48:49]
	v_mov_b32_dpp v214, v32 row_ror:1 row_mask:0xf bank_mask:0xf
	v_mov_b32_dpp v215, v33 row_ror:1 row_mask:0xf bank_mask:0xf
	v_mov_b32_dpp v216, v34 row_ror:1 row_mask:0xf bank_mask:0xf
	v_mov_b32_dpp v217, v35 row_ror:1 row_mask:0xf bank_mask:0xf
	s_nop 1
	v_cndmask_b32_e64 v250, v214, v250, s[48:49]
	v_cndmask_b32_e64 v251, v215, v251, s[48:49]
	v_cndmask_b32_e64 v252, v216, v252, s[48:49]
	v_cndmask_b32_e64 v253, v217, v253, s[48:49]
	v_pk_fma_f32 v[206:207], v[102:103], v[234:235], v[98:99]
	v_pk_fma_f32 v[210:211], v[92:93], v[250:251], v[84:85]
	v_pk_fma_f32 v[208:209], v[104:105], v[236:237], v[100:101]
	v_pk_fma_f32 v[212:213], v[94:95], v[252:253], v[86:87]
	v_pk_fma_f32 v[206:207], v[106:107], v[164:165], v[206:207]
	v_pk_fma_f32 v[210:211], v[88:89], v[168:169], v[210:211]
	v_pk_fma_f32 v[208:209], v[108:109], v[166:167], v[208:209]
	v_pk_fma_f32 v[212:213], v[90:91], v[170:171], v[212:213]
	v_pk_fma_f32 v[206:207], v[110:111], v[60:61], v[206:207]
	v_pk_fma_f32 v[210:211], v[80:81], v[56:57], v[210:211]
	v_pk_fma_f32 v[208:209], v[112:113], v[62:63], v[208:209]
	v_pk_fma_f32 v[212:213], v[82:83], v[58:59], v[212:213]
	v_and_b32_e32 v214, 0x7fffffff, v206
	v_and_b32_e32 v215, 0x7fffffff, v207
	v_pk_mul_f32 v[218:219], v[206:207], v[206:207]
	v_pk_fma_f32 v[214:215], v[214:215], s[6:7], 1.0 op_sel_hi:[1,0,0]
	v_pk_mul_f32 v[218:219], v[218:219], s[36:37] op_sel_hi:[1,0]
	v_rcp_f32_e32 v214, v214
	v_rcp_f32_e32 v215, v215
	v_exp_f32_e32 v218, v218
	v_exp_f32_e32 v219, v219
	v_pk_fma_f32 v[216:217], v[214:215], s[24:25], v[186:187] op_sel_hi:[1,0,0]
	v_max_f32_e32 v220, 0, v206
	v_pk_fma_f32 v[216:217], v[214:215], v[216:217], s[28:29] op_sel_hi:[1,1,0]
	v_max_f32_e32 v221, 0, v207
	v_pk_fma_f32 v[216:217], v[214:215], v[216:217], s[30:31] op_sel_hi:[1,1,0]
	s_nop 0
	v_pk_fma_f32 v[216:217], v[214:215], v[216:217], s[34:35] op_sel_hi:[1,1,0]
	s_nop 0
	v_pk_mul_f32 v[216:217], v[214:215], v[216:217]
	s_nop 0
	v_pk_mul_f32 v[216:217], v[218:219], v[216:217]
	s_nop 0
	v_fma_f32 v206, -|v206|, v216, v220
	v_fma_f32 v207, -|v207|, v217, v221
	v_mul_f32_e32 v206, v210, v206
	v_mul_f32_e32 v207, v211, v207
	v_and_b32_e32 v214, 0x7fffffff, v208
	v_and_b32_e32 v215, 0x7fffffff, v209
	v_pk_mul_f32 v[218:219], v[208:209], v[208:209]
	v_pk_fma_f32 v[214:215], v[214:215], s[6:7], 1.0 op_sel_hi:[1,0,0]
	v_pk_mul_f32 v[218:219], v[218:219], s[36:37] op_sel_hi:[1,0]
	v_rcp_f32_e32 v214, v214
	v_rcp_f32_e32 v215, v215
	v_exp_f32_e32 v218, v218
	v_exp_f32_e32 v219, v219
	v_pk_fma_f32 v[216:217], v[214:215], s[24:25], v[186:187] op_sel_hi:[1,0,0]
	v_max_f32_e32 v220, 0, v208
	v_pk_fma_f32 v[216:217], v[214:215], v[216:217], s[28:29] op_sel_hi:[1,1,0]
	v_max_f32_e32 v221, 0, v209
	v_pk_fma_f32 v[216:217], v[214:215], v[216:217], s[30:31] op_sel_hi:[1,1,0]
	s_nop 0
	v_pk_fma_f32 v[216:217], v[214:215], v[216:217], s[34:35] op_sel_hi:[1,1,0]
	s_nop 0
	v_pk_mul_f32 v[216:217], v[214:215], v[216:217]
	s_nop 0
	v_pk_mul_f32 v[216:217], v[218:219], v[216:217]
	s_nop 0
	v_fma_f32 v208, -|v208|, v216, v220
	v_fma_f32 v209, -|v209|, v217, v221
	v_mul_f32_e32 v208, v212, v208
	v_mul_f32_e32 v209, v213, v209
	v_mov_b64_e32 v[218:219], v[190:191]
	v_cvt_pk_bf16_f32 v220, v206, v207
	v_cvt_pk_bf16_f32 v221, v208, v209
	v_lshl_add_u64 v[126:127], s[56:57], 0, v[184:185]
	s_andn2_b64 exec, exec, s[74:75]
	global_store_dwordx4 v[126:127], v[218:221], off
	s_mov_b64 exec, -1
	s_and_saveexec_b64 s[22:23], s[74:75]
	s_cbranch_execz .Lmy_p5_8
	s_lshr_b32 s18, s16, 6
	s_add_i32 s18, s18, 0
	s_mul_i32 s18, s18, 0x5800
	s_mov_b32 s19, 0
	v_lshlrev_b64 v[214:215], 2, v[182:183]
	v_lshl_add_u64 v[214:215], s[18:19], 0, v[214:215]
	v_lshl_add_u64 v[214:215], s[92:93], 0, v[214:215]
	global_store_dwordx4 v[214:215], v[60:63], off offset:16
	v_lshl_add_u64 v[216:217], v[214:215], 0, s[52:53]
	global_store_dwordx4 v[216:217], v[56:59], off offset:3088
; __device__ __forceinline__ unsigned cvt_pk_bf16(float lo, float hi) { unsigned r; asm volatile("v_cvt_pk_bf16_f32 %0, %1, %2" : "=v"(r) : "v"(lo), "v"(hi)); return r; }
; __device__ __forceinline__ float ror1(float x) { return __builtin_bit_cast(float, __builtin_amdgcn_update_dpp(0, __builtin_bit_cast(int, x), 0x121, 0xf, 0xf, false)); }
; __device__ __forceinline__ f32x2 gelu_pk(f32x2 v) {
;     const f32x2 av = __builtin_elementwise_abs(v), d = av * 0.2316418882f + 1.0f;
;     f32x2 t; t.x = __builtin_amdgcn_rcpf(d.x); t.y = __builtin_amdgcn_rcpf(d.y);
;     f32x2 q = t * 0.5307027145f + (-0.7265760135f); q = q * t + 0.7107068705f; q = q * t + (-0.142248368f); q = q * t + 0.127414796f; q = q * t;
;     const f32x2 s = (v * v) * (-0.72134752044f);
;     f32x2 e; e.x = __builtin_amdgcn_exp2f(s.x); e.y = __builtin_amdgcn_exp2f(s.y);
;     const f32x2 m = v * (q * e), r = v - m;
;     f32x2 o; o.x = v.x < 0.f ? m.x : r.x; o.y = v.y < 0.f ? m.y : r.y; return o;
;     __device__ __forceinline__ void operator()(AccT& acc, const Unit& u, int wr, int wc, int fr, int fq) const {
;     ...
;                     const f32x4 cg_ = acc[ai][0][m][n], cv_ = acc[ai][1][m][n];
;                     f32x4 p1g, p2g, p1v, p2v;
; #pragma unroll
;                     for (int j = 0; j < 4; ++j) {
;                         p1g[j] = ror1(fr == 15 ? hg[j] : cg_[j]); p2g[j] = ror2(fr >= 14 ? hg[j] : cg_[j]);
;                         p1v[j] = ror1(fr == 15 ? hv[j] : cv_[j]); p2v[j] = ror2(fr >= 14 ? hv[j] : cv_[j]);
;                     }
;                     const f32x4 hcg = bg + w0g * p2g + w1g * p1g + w2g * cg_;
;                     const f32x4 hcv = bv + w0v * p2v + w1v * p1v + w2v * cv_;
;                     const f32x2 ga = gelu_pk((f32x2){hcg[0], hcg[1]}), gb2 = gelu_pk((f32x2){hcg[2], hcg[3]});
;                     u32x2 w; w.x = cvt_pk_bf16(ga.x * hcv[0], ga.y * hcv[1]); w.y = cvt_pk_bf16(gb2.x * hcv[2], gb2.y * hcv[3]);
;                     const int t = tstart + rl;
;                     if (n == 0) stash[ai][m] = w;
;                     else if (rl >= 2) *(u32x4*)(U + (size_t)(arow0 + rl) * FF + colg0) = (u32x4){stash[ai][m].x, stash[ai][m].y, w.x, w.y};
;                     if (rl < 2 || rl >= 254) { float* hp = halo + ((size_t)u.pm * 4 + (rl < 2 ? rl : rl - 252)) * FF2; *(f32x4*)(hp + colg) = cg_; *(f32x4*)(hp + colv) = cv_; }
.Lmy_p5_8:
	s_or_b64 exec, exec, s[22:23]
	v_pk_fma_f32 v[206:207], v[102:103], v[164:165], v[98:99]
	v_pk_fma_f32 v[210:211], v[92:93], v[168:169], v[84:85]
	v_pk_fma_f32 v[208:209], v[104:105], v[166:167], v[100:101]
	v_pk_fma_f32 v[212:213], v[94:95], v[170:171], v[86:87]
	v_pk_fma_f32 v[206:207], v[106:107], v[60:61], v[206:207]
	v_pk_fma_f32 v[210:211], v[88:89], v[56:57], v[210:211]
	v_pk_fma_f32 v[208:209], v[108:109], v[62:63], v[208:209]
	v_pk_fma_f32 v[212:213], v[90:91], v[58:59], v[212:213]
	v_pk_fma_f32 v[206:207], v[110:111], v[52:53], v[206:207]
	v_pk_fma_f32 v[210:211], v[80:81], v[40:41], v[210:211]
	v_pk_fma_f32 v[208:209], v[112:113], v[54:55], v[208:209]
	v_pk_fma_f32 v[212:213], v[82:83], v[42:43], v[212:213]
	v_and_b32_e32 v214, 0x7fffffff, v206
	v_and_b32_e32 v215, 0x7fffffff, v207
	v_pk_mul_f32 v[218:219], v[206:207], v[206:207]
	v_pk_fma_f32 v[214:215], v[214:215], s[6:7], 1.0 op_sel_hi:[1,0,0]
	v_pk_mul_f32 v[218:219], v[218:219], s[36:37] op_sel_hi:[1,0]
	v_rcp_f32_e32 v214, v214
	v_rcp_f32_e32 v215, v215
	v_exp_f32_e32 v218, v218
	v_exp_f32_e32 v219, v219
	v_pk_fma_f32 v[216:217], v[214:215], s[24:25], v[186:187] op_sel_hi:[1,0,0]
	v_max_f32_e32 v220, 0, v206
	v_pk_fma_f32 v[216:217], v[214:215], v[216:217], s[28:29] op_sel_hi:[1,1,0]
	v_max_f32_e32 v221, 0, v207
	v_pk_fma_f32 v[216:217], v[214:215], v[216:217], s[30:31] op_sel_hi:[1,1,0]
	s_nop 0
	v_pk_fma_f32 v[216:217], v[214:215], v[216:217], s[34:35] op_sel_hi:[1,1,0]
	s_nop 0
	v_pk_mul_f32 v[216:217], v[214:215], v[216:217]
	s_nop 0
	v_pk_mul_f32 v[216:217], v[218:219], v[216:217]
	s_nop 0
	v_fma_f32 v206, -|v206|, v216, v220
	v_fma_f32 v207, -|v207|, v217, v221
	v_mul_f32_e32 v206, v210, v206
	v_mul_f32_e32 v207, v211, v207
	v_and_b32_e32 v214, 0x7fffffff, v208
	v_and_b32_e32 v215, 0x7fffffff, v209
	v_pk_mul_f32 v[218:219], v[208:209], v[208:209]
	v_pk_fma_f32 v[214:215], v[214:215], s[6:7], 1.0 op_sel_hi:[1,0,0]
	v_pk_mul_f32 v[218:219], v[218:219], s[36:37] op_sel_hi:[1,0]
	v_rcp_f32_e32 v214, v214
	v_rcp_f32_e32 v215, v215
	v_exp_f32_e32 v218, v218
	v_exp_f32_e32 v219, v219
	v_pk_fma_f32 v[216:217], v[214:215], s[24:25], v[186:187] op_sel_hi:[1,0,0]
	v_max_f32_e32 v220, 0, v208
	v_pk_fma_f32 v[216:217], v[214:215], v[216:217], s[28:29] op_sel_hi:[1,1,0]
	v_max_f32_e32 v221, 0, v209
	v_pk_fma_f32 v[216:217], v[214:215], v[216:217], s[30:31] op_sel_hi:[1,1,0]
	s_nop 0
	v_pk_fma_f32 v[216:217], v[214:215], v[216:217], s[34:35] op_sel_hi:[1,1,0]
	s_nop 0
	v_pk_mul_f32 v[216:217], v[214:215], v[216:217]
	s_nop 0
	v_pk_mul_f32 v[216:217], v[218:219], v[216:217]
	s_nop 0
	v_fma_f32 v208, -|v208|, v216, v220
	v_fma_f32 v209, -|v209|, v217, v221
	v_mul_f32_e32 v208, v212, v208
	v_mul_f32_e32 v209, v213, v209
	v_mov_b64_e32 v[218:219], v[238:239]
	v_cvt_pk_bf16_f32 v220, v206, v207
	v_cvt_pk_bf16_f32 v221, v208, v209
	v_lshl_add_u64 v[126:127], s[58:59], 0, v[184:185]
	s_andn2_b64 exec, exec, s[74:75]
	global_store_dwordx4 v[126:127], v[218:221], off
	s_mov_b64 exec, -1
	s_and_saveexec_b64 s[22:23], s[74:75]
	s_cbranch_execz .Lmy_p5_9
	s_lshr_b32 s18, s16, 6
	s_add_i32 s18, s18, 1
	s_mul_i32 s18, s18, 0x5800
	s_mov_b32 s19, 0
	v_lshlrev_b64 v[214:215], 2, v[182:183]
	v_lshl_add_u64 v[214:215], s[18:19], 0, v[214:215]
	v_lshl_add_u64 v[214:215], s[92:93], 0, v[214:215]
	global_store_dwordx4 v[214:215], v[52:55], off offset:16
	v_lshl_add_u64 v[216:217], v[214:215], 0, s[52:53]
	global_store_dwordx4 v[216:217], v[40:43], off offset:3088
.Lmy_p5_9:
	s_or_b64 exec, exec, s[22:23]
	v_pk_fma_f32 v[206:207], v[102:103], v[60:61], v[98:99]
	v_pk_fma_f32 v[210:211], v[92:93], v[56:57], v[84:85]
	v_pk_fma_f32 v[208:209], v[104:105], v[62:63], v[100:101]
	v_pk_fma_f32 v[212:213], v[94:95], v[58:59], v[86:87]
	v_pk_fma_f32 v[206:207], v[106:107], v[52:53], v[206:207]
	v_pk_fma_f32 v[210:211], v[88:89], v[40:41], v[210:211]
	v_pk_fma_f32 v[208:209], v[108:109], v[54:55], v[208:209]
	v_pk_fma_f32 v[212:213], v[90:91], v[42:43], v[212:213]
	v_pk_fma_f32 v[206:207], v[110:111], v[36:37], v[206:207]
	v_pk_fma_f32 v[210:211], v[80:81], v[32:33], v[210:211]
	v_pk_fma_f32 v[208:209], v[112:113], v[38:39], v[208:209]
	v_pk_fma_f32 v[212:213], v[82:83], v[34:35], v[212:213]
	v_and_b32_e32 v214, 0x7fffffff, v206
	v_and_b32_e32 v215, 0x7fffffff, v207
	v_pk_mul_f32 v[218:219], v[206:207], v[206:207]
	v_pk_fma_f32 v[214:215], v[214:215], s[6:7], 1.0 op_sel_hi:[1,0,0]
	v_pk_mul_f32 v[218:219], v[218:219], s[36:37] op_sel_hi:[1,0]
	v_rcp_f32_e32 v214, v214
	v_rcp_f32_e32 v215, v215
	v_exp_f32_e32 v218, v218
	v_exp_f32_e32 v219, v219
	v_pk_fma_f32 v[216:217], v[214:215], s[24:25], v[186:187] op_sel_hi:[1,0,0]
	v_max_f32_e32 v220, 0, v206
	v_pk_fma_f32 v[216:217], v[214:215], v[216:217], s[28:29] op_sel_hi:[1,1,0]
	v_max_f32_e32 v221, 0, v207
	v_pk_fma_f32 v[216:217], v[214:215], v[216:217], s[30:31] op_sel_hi:[1,1,0]
	s_nop 0
	v_pk_fma_f32 v[216:217], v[214:215], v[216:217], s[34:35] op_sel_hi:[1,1,0]
	s_nop 0
	v_pk_mul_f32 v[216:217], v[214:215], v[216:217]
	s_nop 0
	v_pk_mul_f32 v[216:217], v[218:219], v[216:217]
	s_nop 0
	v_fma_f32 v206, -|v206|, v216, v220
	v_fma_f32 v207, -|v207|, v217, v221
	v_mul_f32_e32 v206, v210, v206
	v_mul_f32_e32 v207, v211, v207
	v_and_b32_e32 v214, 0x7fffffff, v208
	v_and_b32_e32 v215, 0x7fffffff, v209
	v_pk_mul_f32 v[218:219], v[208:209], v[208:209]
	v_pk_fma_f32 v[214:215], v[214:215], s[6:7], 1.0 op_sel_hi:[1,0,0]
	v_pk_mul_f32 v[218:219], v[218:219], s[36:37] op_sel_hi:[1,0]
	v_rcp_f32_e32 v214, v214
	v_rcp_f32_e32 v215, v215
	v_exp_f32_e32 v218, v218
	v_exp_f32_e32 v219, v219
	v_pk_fma_f32 v[216:217], v[214:215], s[24:25], v[186:187] op_sel_hi:[1,0,0]
; #define LAS __attribute__((address_space(3)))
; __device__ __forceinline__ f32x2 gelu_pk(f32x2 v) {
;     const f32x2 av = __builtin_elementwise_abs(v), d = av * 0.2316418882f + 1.0f;
;     f32x2 t; t.x = __builtin_amdgcn_rcpf(d.x); t.y = __builtin_amdgcn_rcpf(d.y);
;     f32x2 q = t * 0.5307027145f + (-0.7265760135f); q = q * t + 0.7107068705f; q = q * t + (-0.142248368f); q = q * t + 0.127414796f; q = q * t;
;     const f32x2 s = (v * v) * (-0.72134752044f);
;     f32x2 e; e.x = __builtin_amdgcn_exp2f(s.x); e.y = __builtin_amdgcn_exp2f(s.y);
;     const f32x2 m = v * (q * e), r = v - m;
;     f32x2 o; o.x = v.x < 0.f ? m.x : r.x; o.y = v.y < 0.f ? m.y : r.y; return o;
;     __device__ __forceinline__ void operator()(AccT& acc, const Unit& u, int wr, int wc, int fr, int fq) const {
;     ...
;                 if (s > 0 && fr >= 14) {
;                     hg = *(const LAS f32x4*)(xch + (((s - 1) * 2 + (fr - 14)) * 256 + wc * 32 + fq * 8 + n * 4));
;                     hv = *(const LAS f32x4*)(xch + (((s - 1) * 2 + (fr - 14)) * 256 + 128 + wc * 32 + fq * 8 + n * 4));
;                 }
; #pragma unroll
;                 for (int m = 0; m < 4; ++m) {
;                     const int rl = ai * 128 + wr * 64 + m * 16 + fr;
;                     const f32x4 cg_ = acc[ai][0][m][n], cv_ = acc[ai][1][m][n];
;                     f32x4 p1g, p2g, p1v, p2v;
; #pragma unroll
;                     for (int j = 0; j < 4; ++j) {
;                         p1g[j] = ror1(fr == 15 ? hg[j] : cg_[j]); p2g[j] = ror2(fr >= 14 ? hg[j] : cg_[j]);
;                         p1v[j] = ror1(fr == 15 ? hv[j] : cv_[j]); p2v[j] = ror2(fr >= 14 ? hv[j] : cv_[j]);
;                     }
;                     const f32x4 hcg = bg + w0g * p2g + w1g * p1g + w2g * cg_;
;                     const f32x4 hcv = bv + w0v * p2v + w1v * p1v + w2v * cv_;
;                     const f32x2 ga = gelu_pk((f32x2){hcg[0], hcg[1]}), gb2 = gelu_pk((f32x2){hcg[2], hcg[3]});
;                     u32x2 w; w.x = cvt_pk_bf16(ga.x * hcv[0], ga.y * hcv[1]); w.y = cvt_pk_bf16(gb2.x * hcv[2], gb2.y * hcv[3]);
;                     const int t = tstart + rl;
;                     if (n == 0) stash[ai][m] = w;
;                     else if (rl >= 2) *(u32x4*)(U + (size_t)(arow0 + rl) * FF + colg0) = (u32x4){stash[ai][m].x, stash[ai][m].y, w.x, w.y};
	v_max_f32_e32 v220, 0, v208
	v_pk_fma_f32 v[216:217], v[214:215], v[216:217], s[28:29] op_sel_hi:[1,1,0]
	v_max_f32_e32 v221, 0, v209
	v_pk_fma_f32 v[216:217], v[214:215], v[216:217], s[30:31] op_sel_hi:[1,1,0]
	s_nop 0
	v_pk_fma_f32 v[216:217], v[214:215], v[216:217], s[34:35] op_sel_hi:[1,1,0]
	s_nop 0
	v_pk_mul_f32 v[216:217], v[214:215], v[216:217]
	s_nop 0
	v_pk_mul_f32 v[216:217], v[218:219], v[216:217]
	s_nop 0
	v_fma_f32 v208, -|v208|, v216, v220
	v_fma_f32 v209, -|v209|, v217, v221
	v_mul_f32_e32 v208, v212, v208
	v_mul_f32_e32 v209, v213, v209
	v_mov_b64_e32 v[218:219], v[160:161]
	v_cvt_pk_bf16_f32 v220, v206, v207
	v_cvt_pk_bf16_f32 v221, v208, v209
	v_lshl_add_u64 v[126:127], s[60:61], 0, v[184:185]
	global_store_dwordx4 v[126:127], v[218:221], off
	v_pk_fma_f32 v[206:207], v[102:103], v[52:53], v[98:99]
	v_pk_fma_f32 v[210:211], v[92:93], v[40:41], v[84:85]
	v_pk_fma_f32 v[208:209], v[104:105], v[54:55], v[100:101]
	v_pk_fma_f32 v[212:213], v[94:95], v[42:43], v[86:87]
	v_pk_fma_f32 v[206:207], v[106:107], v[36:37], v[206:207]
	v_pk_fma_f32 v[210:211], v[88:89], v[32:33], v[210:211]
	v_pk_fma_f32 v[208:209], v[108:109], v[38:39], v[208:209]
	v_pk_fma_f32 v[212:213], v[90:91], v[34:35], v[212:213]
	v_pk_fma_f32 v[206:207], v[110:111], v[48:49], v[206:207]
	v_pk_fma_f32 v[210:211], v[80:81], v[44:45], v[210:211]
	v_pk_fma_f32 v[208:209], v[112:113], v[50:51], v[208:209]
	v_pk_fma_f32 v[212:213], v[82:83], v[46:47], v[212:213]
	v_and_b32_e32 v214, 0x7fffffff, v206
	v_and_b32_e32 v215, 0x7fffffff, v207
	v_pk_mul_f32 v[218:219], v[206:207], v[206:207]
	v_pk_fma_f32 v[214:215], v[214:215], s[6:7], 1.0 op_sel_hi:[1,0,0]
	v_pk_mul_f32 v[218:219], v[218:219], s[36:37] op_sel_hi:[1,0]
	v_rcp_f32_e32 v214, v214
	v_rcp_f32_e32 v215, v215
	v_exp_f32_e32 v218, v218
	v_exp_f32_e32 v219, v219
	v_pk_fma_f32 v[216:217], v[214:215], s[24:25], v[186:187] op_sel_hi:[1,0,0]
	v_max_f32_e32 v220, 0, v206
	v_pk_fma_f32 v[216:217], v[214:215], v[216:217], s[28:29] op_sel_hi:[1,1,0]
	v_max_f32_e32 v221, 0, v207
	v_pk_fma_f32 v[216:217], v[214:215], v[216:217], s[30:31] op_sel_hi:[1,1,0]
	s_nop 0
	v_pk_fma_f32 v[216:217], v[214:215], v[216:217], s[34:35] op_sel_hi:[1,1,0]
	s_nop 0
	v_pk_mul_f32 v[216:217], v[214:215], v[216:217]
	s_nop 0
	v_pk_mul_f32 v[216:217], v[218:219], v[216:217]
	s_nop 0
	v_fma_f32 v206, -|v206|, v216, v220
	v_fma_f32 v207, -|v207|, v217, v221
	v_mul_f32_e32 v206, v210, v206
	v_mul_f32_e32 v207, v211, v207
	v_and_b32_e32 v214, 0x7fffffff, v208
	v_and_b32_e32 v215, 0x7fffffff, v209
	v_pk_mul_f32 v[218:219], v[208:209], v[208:209]
	v_pk_fma_f32 v[214:215], v[214:215], s[6:7], 1.0 op_sel_hi:[1,0,0]
	v_pk_mul_f32 v[218:219], v[218:219], s[36:37] op_sel_hi:[1,0]
	v_rcp_f32_e32 v214, v214
	v_rcp_f32_e32 v215, v215
	v_exp_f32_e32 v218, v218
	v_exp_f32_e32 v219, v219
	v_pk_fma_f32 v[216:217], v[214:215], s[24:25], v[186:187] op_sel_hi:[1,0,0]
	v_max_f32_e32 v220, 0, v208
	v_pk_fma_f32 v[216:217], v[214:215], v[216:217], s[28:29] op_sel_hi:[1,1,0]
	v_max_f32_e32 v221, 0, v209
	v_pk_fma_f32 v[216:217], v[214:215], v[216:217], s[30:31] op_sel_hi:[1,1,0]
	s_nop 0
	v_pk_fma_f32 v[216:217], v[214:215], v[216:217], s[34:35] op_sel_hi:[1,1,0]
	s_nop 0
	v_pk_mul_f32 v[216:217], v[214:215], v[216:217]
	s_nop 0
	v_pk_mul_f32 v[216:217], v[218:219], v[216:217]
	s_nop 0
	v_fma_f32 v208, -|v208|, v216, v220
	v_fma_f32 v209, -|v209|, v217, v221
	v_mul_f32_e32 v208, v212, v208
	v_mul_f32_e32 v209, v213, v209
	v_mov_b64_e32 v[218:219], v[144:145]
	v_cvt_pk_bf16_f32 v220, v206, v207
	v_cvt_pk_bf16_f32 v221, v208, v209
	v_lshl_add_u64 v[126:127], s[62:63], 0, v[184:185]
	global_store_dwordx4 v[126:127], v[218:221], off
	v_mov_b64_e32 v[164:165], 0
	v_mov_b64_e32 v[166:167], 0
	v_mov_b64_e32 v[168:169], 0
	v_mov_b64_e32 v[170:171], 0
	v_mov_b64_e32 v[234:235], 0
	v_mov_b64_e32 v[236:237], 0
	v_mov_b64_e32 v[250:251], 0
	v_mov_b64_e32 v[252:253], 0
	s_and_saveexec_b64 s[20:21], s[48:49]
	s_cbranch_execz .Lmy_p5_10
	ds_read_b128 v[234:237], v188 offset:4128
	ds_read_b128 v[250:253], v188 offset:4144
	ds_read_b128 v[164:167], v188 offset:4192
	ds_read_b128 v[168:171], v188 offset:4208
.Lmy_p5_10:
	s_or_b64 exec, exec, s[20:21]
	s_waitcnt lgkmcnt(0)
	s_nop 4
	v_mov_b32_dpp v214, v16 row_ror:1 row_mask:0xf bank_mask:0xf
	v_mov_b32_dpp v215, v17 row_ror:1 row_mask:0xf bank_mask:0xf
	v_mov_b32_dpp v216, v18 row_ror:1 row_mask:0xf bank_mask:0xf
	v_mov_b32_dpp v217, v19 row_ror:1 row_mask:0xf bank_mask:0xf
	s_nop 1
	v_cndmask_b32_e64 v164, v214, v164, s[48:49]
	v_cndmask_b32_e64 v165, v215, v165, s[48:49]
	v_cndmask_b32_e64 v166, v216, v166, s[48:49]
	v_cndmask_b32_e64 v167, v217, v167, s[48:49]
	v_mov_b32_dpp v214, v20 row_ror:1 row_mask:0xf bank_mask:0xf
	v_mov_b32_dpp v215, v21 row_ror:1 row_mask:0xf bank_mask:0xf
	v_mov_b32_dpp v216, v22 row_ror:1 row_mask:0xf bank_mask:0xf
	v_mov_b32_dpp v217, v23 row_ror:1 row_mask:0xf bank_mask:0xf
	s_nop 1
	v_cndmask_b32_e64 v168, v214, v168, s[48:49]
	v_cndmask_b32_e64 v169, v215, v169, s[48:49]
	v_cndmask_b32_e64 v170, v216, v170, s[48:49]
	v_cndmask_b32_e64 v171, v217, v171, s[48:49]
	v_mov_b32_dpp v214, v4 row_ror:1 row_mask:0xf bank_mask:0xf
	v_mov_b32_dpp v215, v5 row_ror:1 row_mask:0xf bank_mask:0xf
	v_mov_b32_dpp v216, v6 row_ror:1 row_mask:0xf bank_mask:0xf
	v_mov_b32_dpp v217, v7 row_ror:1 row_mask:0xf bank_mask:0xf
	s_nop 1
	v_cndmask_b32_e64 v234, v214, v234, s[48:49]
	v_cndmask_b32_e64 v235, v215, v235, s[48:49]
	v_cndmask_b32_e64 v236, v216, v236, s[48:49]
	v_cndmask_b32_e64 v237, v217, v237, s[48:49]
	v_mov_b32_dpp v214, v0 row_ror:1 row_mask:0xf bank_mask:0xf
	v_mov_b32_dpp v215, v1 row_ror:1 row_mask:0xf bank_mask:0xf
; __device__ __forceinline__ unsigned cvt_pk_bf16(float lo, float hi) { unsigned r; asm volatile("v_cvt_pk_bf16_f32 %0, %1, %2" : "=v"(r) : "v"(lo), "v"(hi)); return r; }
; __device__ __forceinline__ float ror1(float x) { return __builtin_bit_cast(float, __builtin_amdgcn_update_dpp(0, __builtin_bit_cast(int, x), 0x121, 0xf, 0xf, false)); }
; __device__ __forceinline__ float ror2(float x) { return __builtin_bit_cast(float, __builtin_amdgcn_update_dpp(0, __builtin_bit_cast(int, x), 0x122, 0xf, 0xf, false)); }
; __device__ __forceinline__ f32x2 gelu_pk(f32x2 v) {
;     const f32x2 av = __builtin_elementwise_abs(v), d = av * 0.2316418882f + 1.0f;
;     f32x2 t; t.x = __builtin_amdgcn_rcpf(d.x); t.y = __builtin_amdgcn_rcpf(d.y);
;     f32x2 q = t * 0.5307027145f + (-0.7265760135f); q = q * t + 0.7107068705f; q = q * t + (-0.142248368f); q = q * t + 0.127414796f; q = q * t;
;     const f32x2 s = (v * v) * (-0.72134752044f);
;     f32x2 e; e.x = __builtin_amdgcn_exp2f(s.x); e.y = __builtin_amdgcn_exp2f(s.y);
;     const f32x2 m = v * (q * e), r = v - m;
;     f32x2 o; o.x = v.x < 0.f ? m.x : r.x; o.y = v.y < 0.f ? m.y : r.y; return o;
;     __device__ __forceinline__ void operator()(AccT& acc, const Unit& u, int wr, int wc, int fr, int fq) const {
;     ...
;                     const f32x4 cg_ = acc[ai][0][m][n], cv_ = acc[ai][1][m][n];
;                     f32x4 p1g, p2g, p1v, p2v;
; #pragma unroll
;                     for (int j = 0; j < 4; ++j) {
;                         p1g[j] = ror1(fr == 15 ? hg[j] : cg_[j]); p2g[j] = ror2(fr >= 14 ? hg[j] : cg_[j]);
;                         p1v[j] = ror1(fr == 15 ? hv[j] : cv_[j]); p2v[j] = ror2(fr >= 14 ? hv[j] : cv_[j]);
;                     }
;                     const f32x4 hcg = bg + w0g * p2g + w1g * p1g + w2g * cg_;
;                     const f32x4 hcv = bv + w0v * p2v + w1v * p1v + w2v * cv_;
;                     const f32x2 ga = gelu_pk((f32x2){hcg[0], hcg[1]}), gb2 = gelu_pk((f32x2){hcg[2], hcg[3]});
;                     u32x2 w; w.x = cvt_pk_bf16(ga.x * hcv[0], ga.y * hcv[1]); w.y = cvt_pk_bf16(gb2.x * hcv[2], gb2.y * hcv[3]);
;                     const int t = tstart + rl;
;                     if (n == 0) stash[ai][m] = w;
;                     else if (rl >= 2) *(u32x4*)(U + (size_t)(arow0 + rl) * FF + colg0) = (u32x4){stash[ai][m].x, stash[ai][m].y, w.x, w.y};
	v_mov_b32_dpp v216, v2 row_ror:1 row_mask:0xf bank_mask:0xf
	v_mov_b32_dpp v217, v3 row_ror:1 row_mask:0xf bank_mask:0xf
	s_nop 1
	v_cndmask_b32_e64 v250, v214, v250, s[48:49]
	v_cndmask_b32_e64 v251, v215, v251, s[48:49]
	v_cndmask_b32_e64 v252, v216, v252, s[48:49]
	v_cndmask_b32_e64 v253, v217, v253, s[48:49]
	v_pk_fma_f32 v[206:207], v[102:103], v[234:235], v[98:99]
	v_pk_fma_f32 v[210:211], v[92:93], v[250:251], v[84:85]
	v_pk_fma_f32 v[208:209], v[104:105], v[236:237], v[100:101]
	v_pk_fma_f32 v[212:213], v[94:95], v[252:253], v[86:87]
	v_pk_fma_f32 v[206:207], v[106:107], v[164:165], v[206:207]
	v_pk_fma_f32 v[210:211], v[88:89], v[168:169], v[210:211]
	v_pk_fma_f32 v[208:209], v[108:109], v[166:167], v[208:209]
	v_pk_fma_f32 v[212:213], v[90:91], v[170:171], v[212:213]
	v_pk_fma_f32 v[206:207], v[110:111], v[28:29], v[206:207]
	v_pk_fma_f32 v[210:211], v[80:81], v[24:25], v[210:211]
	v_pk_fma_f32 v[208:209], v[112:113], v[30:31], v[208:209]
	v_pk_fma_f32 v[212:213], v[82:83], v[26:27], v[212:213]
	v_and_b32_e32 v214, 0x7fffffff, v206
	v_and_b32_e32 v215, 0x7fffffff, v207
	v_pk_mul_f32 v[218:219], v[206:207], v[206:207]
	v_pk_fma_f32 v[214:215], v[214:215], s[6:7], 1.0 op_sel_hi:[1,0,0]
	v_pk_mul_f32 v[218:219], v[218:219], s[36:37] op_sel_hi:[1,0]
	v_rcp_f32_e32 v214, v214
	v_rcp_f32_e32 v215, v215
	v_exp_f32_e32 v218, v218
	v_exp_f32_e32 v219, v219
	v_pk_fma_f32 v[216:217], v[214:215], s[24:25], v[186:187] op_sel_hi:[1,0,0]
	v_max_f32_e32 v220, 0, v206
	v_pk_fma_f32 v[216:217], v[214:215], v[216:217], s[28:29] op_sel_hi:[1,1,0]
	v_max_f32_e32 v221, 0, v207
	v_pk_fma_f32 v[216:217], v[214:215], v[216:217], s[30:31] op_sel_hi:[1,1,0]
	s_nop 0
	v_pk_fma_f32 v[216:217], v[214:215], v[216:217], s[34:35] op_sel_hi:[1,1,0]
	s_nop 0
	v_pk_mul_f32 v[216:217], v[214:215], v[216:217]
	s_nop 0
	v_pk_mul_f32 v[216:217], v[218:219], v[216:217]
	s_nop 0
	v_fma_f32 v206, -|v206|, v216, v220
	v_fma_f32 v207, -|v207|, v217, v221
	v_mul_f32_e32 v206, v210, v206
	v_mul_f32_e32 v207, v211, v207
	v_and_b32_e32 v214, 0x7fffffff, v208
	v_and_b32_e32 v215, 0x7fffffff, v209
	v_pk_mul_f32 v[218:219], v[208:209], v[208:209]
	v_pk_fma_f32 v[214:215], v[214:215], s[6:7], 1.0 op_sel_hi:[1,0,0]
	v_pk_mul_f32 v[218:219], v[218:219], s[36:37] op_sel_hi:[1,0]
	v_rcp_f32_e32 v214, v214
	v_rcp_f32_e32 v215, v215
	v_exp_f32_e32 v218, v218
	v_exp_f32_e32 v219, v219
	v_pk_fma_f32 v[216:217], v[214:215], s[24:25], v[186:187] op_sel_hi:[1,0,0]
	v_max_f32_e32 v220, 0, v208
	v_pk_fma_f32 v[216:217], v[214:215], v[216:217], s[28:29] op_sel_hi:[1,1,0]
	v_max_f32_e32 v221, 0, v209
	v_pk_fma_f32 v[216:217], v[214:215], v[216:217], s[30:31] op_sel_hi:[1,1,0]
	s_nop 0
	v_pk_fma_f32 v[216:217], v[214:215], v[216:217], s[34:35] op_sel_hi:[1,1,0]
	s_nop 0
	v_pk_mul_f32 v[216:217], v[214:215], v[216:217]
	s_nop 0
	v_pk_mul_f32 v[216:217], v[218:219], v[216:217]
	s_nop 0
	v_fma_f32 v208, -|v208|, v216, v220
	v_fma_f32 v209, -|v209|, v217, v221
	v_mul_f32_e32 v208, v212, v208
	v_mul_f32_e32 v209, v213, v209
	v_mov_b64_e32 v[218:219], v[156:157]
	v_cvt_pk_bf16_f32 v220, v206, v207
	v_cvt_pk_bf16_f32 v221, v208, v209
	v_lshl_add_u64 v[126:127], s[64:65], 0, v[184:185]
	global_store_dwordx4 v[126:127], v[218:221], off
	v_pk_fma_f32 v[206:207], v[102:103], v[164:165], v[98:99]
	v_pk_fma_f32 v[210:211], v[92:93], v[168:169], v[84:85]
	v_pk_fma_f32 v[208:209], v[104:105], v[166:167], v[100:101]
	v_pk_fma_f32 v[212:213], v[94:95], v[170:171], v[86:87]
	v_pk_fma_f32 v[206:207], v[106:107], v[28:29], v[206:207]
	v_pk_fma_f32 v[210:211], v[88:89], v[24:25], v[210:211]
	v_pk_fma_f32 v[208:209], v[108:109], v[30:31], v[208:209]
	v_pk_fma_f32 v[212:213], v[90:91], v[26:27], v[212:213]
	v_pk_fma_f32 v[206:207], v[110:111], v[12:13], v[206:207]
	v_pk_fma_f32 v[210:211], v[80:81], v[8:9], v[210:211]
	v_pk_fma_f32 v[208:209], v[112:113], v[14:15], v[208:209]
	v_pk_fma_f32 v[212:213], v[82:83], v[10:11], v[212:213]
	v_and_b32_e32 v214, 0x7fffffff, v206
	v_and_b32_e32 v215, 0x7fffffff, v207
	v_pk_mul_f32 v[218:219], v[206:207], v[206:207]
	v_pk_fma_f32 v[214:215], v[214:215], s[6:7], 1.0 op_sel_hi:[1,0,0]
	v_pk_mul_f32 v[218:219], v[218:219], s[36:37] op_sel_hi:[1,0]
	v_rcp_f32_e32 v214, v214
	v_rcp_f32_e32 v215, v215
	v_exp_f32_e32 v218, v218
	v_exp_f32_e32 v219, v219
	v_pk_fma_f32 v[216:217], v[214:215], s[24:25], v[186:187] op_sel_hi:[1,0,0]
	v_max_f32_e32 v220, 0, v206
	v_pk_fma_f32 v[216:217], v[214:215], v[216:217], s[28:29] op_sel_hi:[1,1,0]
	v_max_f32_e32 v221, 0, v207
	v_pk_fma_f32 v[216:217], v[214:215], v[216:217], s[30:31] op_sel_hi:[1,1,0]
	s_nop 0
	v_pk_fma_f32 v[216:217], v[214:215], v[216:217], s[34:35] op_sel_hi:[1,1,0]
	s_nop 0
	v_pk_mul_f32 v[216:217], v[214:215], v[216:217]
	s_nop 0
	v_pk_mul_f32 v[216:217], v[218:219], v[216:217]
	s_nop 0
	v_fma_f32 v206, -|v206|, v216, v220
	v_fma_f32 v207, -|v207|, v217, v221
	v_mul_f32_e32 v206, v210, v206
	v_mul_f32_e32 v207, v211, v207
	v_and_b32_e32 v214, 0x7fffffff, v208
	v_and_b32_e32 v215, 0x7fffffff, v209
	v_pk_mul_f32 v[218:219], v[208:209], v[208:209]
	v_pk_fma_f32 v[214:215], v[214:215], s[6:7], 1.0 op_sel_hi:[1,0,0]
	v_pk_mul_f32 v[218:219], v[218:219], s[36:37] op_sel_hi:[1,0]
	v_rcp_f32_e32 v214, v214
	v_rcp_f32_e32 v215, v215
	v_exp_f32_e32 v218, v218
	v_exp_f32_e32 v219, v219
	v_pk_fma_f32 v[216:217], v[214:215], s[24:25], v[186:187] op_sel_hi:[1,0,0]
	v_max_f32_e32 v220, 0, v208
	v_pk_fma_f32 v[216:217], v[214:215], v[216:217], s[28:29] op_sel_hi:[1,1,0]
	v_max_f32_e32 v221, 0, v209
	v_pk_fma_f32 v[216:217], v[214:215], v[216:217], s[30:31] op_sel_hi:[1,1,0]
	s_nop 0
	v_pk_fma_f32 v[216:217], v[214:215], v[216:217], s[34:35] op_sel_hi:[1,1,0]
; __device__ __forceinline__ unsigned cvt_pk_bf16(float lo, float hi) { unsigned r; asm volatile("v_cvt_pk_bf16_f32 %0, %1, %2" : "=v"(r) : "v"(lo), "v"(hi)); return r; }
; __device__ __forceinline__ f32x2 gelu_pk(f32x2 v) {
;     const f32x2 av = __builtin_elementwise_abs(v), d = av * 0.2316418882f + 1.0f;
;     f32x2 t; t.x = __builtin_amdgcn_rcpf(d.x); t.y = __builtin_amdgcn_rcpf(d.y);
;     f32x2 q = t * 0.5307027145f + (-0.7265760135f); q = q * t + 0.7107068705f; q = q * t + (-0.142248368f); q = q * t + 0.127414796f; q = q * t;
;     const f32x2 s = (v * v) * (-0.72134752044f);
;     f32x2 e; e.x = __builtin_amdgcn_exp2f(s.x); e.y = __builtin_amdgcn_exp2f(s.y);
;     const f32x2 m = v * (q * e), r = v - m;
;     f32x2 o; o.x = v.x < 0.f ? m.x : r.x; o.y = v.y < 0.f ? m.y : r.y; return o;
;     __device__ __forceinline__ void operator()(AccT& acc, const Unit& u, int wr, int wc, int fr, int fq) const {
;     ...
;                     const f32x4 hcg = bg + w0g * p2g + w1g * p1g + w2g * cg_;
;                     const f32x4 hcv = bv + w0v * p2v + w1v * p1v + w2v * cv_;
;                     const f32x2 ga = gelu_pk((f32x2){hcg[0], hcg[1]}), gb2 = gelu_pk((f32x2){hcg[2], hcg[3]});
;                     u32x2 w; w.x = cvt_pk_bf16(ga.x * hcv[0], ga.y * hcv[1]); w.y = cvt_pk_bf16(gb2.x * hcv[2], gb2.y * hcv[3]);
;                     const int t = tstart + rl;
;                     if (n == 0) stash[ai][m] = w;
;                     else if (rl >= 2) *(u32x4*)(U + (size_t)(arow0 + rl) * FF + colg0) = (u32x4){stash[ai][m].x, stash[ai][m].y, w.x, w.y};
;                     if (rl < 2 || rl >= 254) { float* hp = halo + ((size_t)u.pm * 4 + (rl < 2 ? rl : rl - 252)) * FF2; *(f32x4*)(hp + colg) = cg_; *(f32x4*)(hp + colv) = cv_; }
;                     if (t >= SEQ - 2) { float* cp = conv_p + (size_t)(b * 2 + (t - (SEQ - 2))) * FF2; *(f32x4*)(cp + colg) = cg_; *(f32x4*)(cp + colv) = cv_; }
	s_nop 0
	v_pk_mul_f32 v[216:217], v[214:215], v[216:217]
	s_nop 0
	v_pk_mul_f32 v[216:217], v[218:219], v[216:217]
	s_nop 0
	v_fma_f32 v208, -|v208|, v216, v220
	v_fma_f32 v209, -|v209|, v217, v221
	v_mul_f32_e32 v208, v212, v208
	v_mul_f32_e32 v209, v213, v209
	v_mov_b64_e32 v[218:219], v[118:119]
	v_cvt_pk_bf16_f32 v220, v206, v207
	v_cvt_pk_bf16_f32 v221, v208, v209
	v_lshl_add_u64 v[126:127], s[66:67], 0, v[184:185]
	global_store_dwordx4 v[126:127], v[218:221], off
	v_pk_fma_f32 v[206:207], v[102:103], v[28:29], v[98:99]
	v_pk_fma_f32 v[210:211], v[92:93], v[24:25], v[84:85]
	v_pk_fma_f32 v[208:209], v[104:105], v[30:31], v[100:101]
	v_pk_fma_f32 v[212:213], v[94:95], v[26:27], v[86:87]
	v_pk_fma_f32 v[206:207], v[106:107], v[12:13], v[206:207]
	v_pk_fma_f32 v[210:211], v[88:89], v[8:9], v[210:211]
	v_pk_fma_f32 v[208:209], v[108:109], v[14:15], v[208:209]
	v_pk_fma_f32 v[212:213], v[90:91], v[10:11], v[212:213]
	v_pk_fma_f32 v[206:207], v[110:111], v[4:5], v[206:207]
	v_pk_fma_f32 v[210:211], v[80:81], v[0:1], v[210:211]
	v_pk_fma_f32 v[208:209], v[112:113], v[6:7], v[208:209]
	v_pk_fma_f32 v[212:213], v[82:83], v[2:3], v[212:213]
	v_and_b32_e32 v214, 0x7fffffff, v206
	v_and_b32_e32 v215, 0x7fffffff, v207
	v_pk_mul_f32 v[218:219], v[206:207], v[206:207]
	v_pk_fma_f32 v[214:215], v[214:215], s[6:7], 1.0 op_sel_hi:[1,0,0]
	v_pk_mul_f32 v[218:219], v[218:219], s[36:37] op_sel_hi:[1,0]
	v_rcp_f32_e32 v214, v214
	v_rcp_f32_e32 v215, v215
	v_exp_f32_e32 v218, v218
	v_exp_f32_e32 v219, v219
	v_pk_fma_f32 v[216:217], v[214:215], s[24:25], v[186:187] op_sel_hi:[1,0,0]
	v_max_f32_e32 v220, 0, v206
	v_pk_fma_f32 v[216:217], v[214:215], v[216:217], s[28:29] op_sel_hi:[1,1,0]
	v_max_f32_e32 v221, 0, v207
	v_pk_fma_f32 v[216:217], v[214:215], v[216:217], s[30:31] op_sel_hi:[1,1,0]
	s_nop 0
	v_pk_fma_f32 v[216:217], v[214:215], v[216:217], s[34:35] op_sel_hi:[1,1,0]
	s_nop 0
	v_pk_mul_f32 v[216:217], v[214:215], v[216:217]
	s_nop 0
	v_pk_mul_f32 v[216:217], v[218:219], v[216:217]
	s_nop 0
	v_fma_f32 v206, -|v206|, v216, v220
	v_fma_f32 v207, -|v207|, v217, v221
	v_mul_f32_e32 v206, v210, v206
	v_mul_f32_e32 v207, v211, v207
	v_and_b32_e32 v214, 0x7fffffff, v208
	v_and_b32_e32 v215, 0x7fffffff, v209
	v_pk_mul_f32 v[218:219], v[208:209], v[208:209]
	v_pk_fma_f32 v[214:215], v[214:215], s[6:7], 1.0 op_sel_hi:[1,0,0]
	v_pk_mul_f32 v[218:219], v[218:219], s[36:37] op_sel_hi:[1,0]
	v_rcp_f32_e32 v214, v214
	v_rcp_f32_e32 v215, v215
	v_exp_f32_e32 v218, v218
	v_exp_f32_e32 v219, v219
	v_pk_fma_f32 v[216:217], v[214:215], s[24:25], v[186:187] op_sel_hi:[1,0,0]
	v_max_f32_e32 v220, 0, v208
	v_pk_fma_f32 v[216:217], v[214:215], v[216:217], s[28:29] op_sel_hi:[1,1,0]
	v_max_f32_e32 v221, 0, v209
	v_pk_fma_f32 v[216:217], v[214:215], v[216:217], s[30:31] op_sel_hi:[1,1,0]
	s_nop 0
	v_pk_fma_f32 v[216:217], v[214:215], v[216:217], s[34:35] op_sel_hi:[1,1,0]
	s_nop 0
	v_pk_mul_f32 v[216:217], v[214:215], v[216:217]
	s_nop 0
	v_pk_mul_f32 v[216:217], v[218:219], v[216:217]
	s_nop 0
	v_fma_f32 v208, -|v208|, v216, v220
	v_fma_f32 v209, -|v209|, v217, v221
	v_mul_f32_e32 v208, v212, v208
	v_mul_f32_e32 v209, v213, v209
	v_mov_b64_e32 v[218:219], v[140:141]
	v_cvt_pk_bf16_f32 v220, v206, v207
	v_cvt_pk_bf16_f32 v221, v208, v209
	v_lshl_add_u64 v[126:127], s[68:69], 0, v[184:185]
	global_store_dwordx4 v[126:127], v[218:221], off
	s_and_saveexec_b64 s[22:23], s[76:77]
	s_cbranch_execz .Lmy_p5_11
	s_lshr_b32 s18, s16, 6
	s_add_i32 s18, s18, 2
	s_mul_i32 s18, s18, 0x5800
	s_mov_b32 s19, 0
	v_lshlrev_b64 v[214:215], 2, v[182:183]
	v_lshl_add_u64 v[214:215], s[18:19], 0, v[214:215]
	v_lshl_add_u64 v[214:215], s[92:93], 0, v[214:215]
	global_store_dwordx4 v[214:215], v[4:7], off offset:16
	v_lshl_add_u64 v[216:217], v[214:215], 0, s[52:53]
	global_store_dwordx4 v[216:217], v[0:3], off offset:3088
	s_bfe_u32 s18, s16, 0x60008
	s_cmp_eq_u32 s18, 63
	s_cbranch_scc0 .Lmy_p5_11
	s_lshr_b32 s18, s16, 14
	s_lshl_b32 s18, s18, 1
	s_add_i32 s18, s18, 0
	s_mul_i32 s18, s18, 0x5800
	s_mov_b32 s19, 0
	v_lshlrev_b64 v[214:215], 2, v[182:183]
	v_lshl_add_u64 v[214:215], s[18:19], 0, v[214:215]
	v_lshl_add_u64 v[214:215], s[0:1], 0, v[214:215]
	global_store_dwordx4 v[214:215], v[4:7], off offset:16
	v_lshl_add_u64 v[216:217], v[214:215], 0, s[52:53]
	global_store_dwordx4 v[216:217], v[0:3], off offset:3088
; __device__ __forceinline__ unsigned cvt_pk_bf16(float lo, float hi) { unsigned r; asm volatile("v_cvt_pk_bf16_f32 %0, %1, %2" : "=v"(r) : "v"(lo), "v"(hi)); return r; }
; #define PG8_BAR __builtin_amdgcn_s_barrier()
; template <class Epi, class Sched>
; __device__ __forceinline__ void gemm_phase(LAS unsigned char* lds, const Gemm g, const Sched& S, const Epi& E) {
;     ...
;         if (!has_next) break;
;         if (!epi_keep_acc(E, cur)) {
; #pragma unroll
;         for (int a = 0; a < 2; ++a)
; #pragma unroll
;             for (int b = 0; b < 2; ++b)
; #pragma unroll
;                 for (int m = 0; m < 4; ++m)
; #pragma unroll
;                     for (int n = 0; n < 2; ++n) acc[a][b][m][n] = (f32x4){0.f, 0.f, 0.f, 0.f};
;         }
;         cur = nxt; cA = nA; cB = nB; ++ui;
;         if (wr == 1) PG8_BAR;
;     __device__ __forceinline__ void operator()(AccT& acc, const Unit& u, int wr, int wc, int fr, int fq) const {
;     ...
;                     const f32x4 hcg = bg + w0g * p2g + w1g * p1g + w2g * cg_;
;                     const f32x4 hcv = bv + w0v * p2v + w1v * p1v + w2v * cv_;
;                     const f32x2 ga = gelu_pk((f32x2){hcg[0], hcg[1]}), gb2 = gelu_pk((f32x2){hcg[2], hcg[3]});
;                     u32x2 w; w.x = cvt_pk_bf16(ga.x * hcv[0], ga.y * hcv[1]); w.y = cvt_pk_bf16(gb2.x * hcv[2], gb2.y * hcv[3]);
;                     const int t = tstart + rl;
;                     if (n == 0) stash[ai][m] = w;
;                     else if (rl >= 2) *(u32x4*)(U + (size_t)(arow0 + rl) * FF + colg0) = (u32x4){stash[ai][m].x, stash[ai][m].y, w.x, w.y};
;                     if (rl < 2 || rl >= 254) { float* hp = halo + ((size_t)u.pm * 4 + (rl < 2 ? rl : rl - 252)) * FF2; *(f32x4*)(hp + colg) = cg_; *(f32x4*)(hp + colv) = cv_; }
;                     if (t >= SEQ - 2) { float* cp = conv_p + (size_t)(b * 2 + (t - (SEQ - 2))) * FF2; *(f32x4*)(cp + colg) = cg_; *(f32x4*)(cp + colv) = cv_; }
.Lmy_p5_11:
	s_or_b64 exec, exec, s[22:23]
	v_pk_fma_f32 v[206:207], v[102:103], v[12:13], v[98:99]
	v_pk_fma_f32 v[210:211], v[92:93], v[8:9], v[84:85]
	v_pk_fma_f32 v[208:209], v[104:105], v[14:15], v[100:101]
	v_pk_fma_f32 v[212:213], v[94:95], v[10:11], v[86:87]
	v_pk_fma_f32 v[206:207], v[106:107], v[4:5], v[206:207]
	v_pk_fma_f32 v[210:211], v[88:89], v[0:1], v[210:211]
	v_pk_fma_f32 v[208:209], v[108:109], v[6:7], v[208:209]
	v_pk_fma_f32 v[212:213], v[90:91], v[2:3], v[212:213]
	v_pk_fma_f32 v[206:207], v[110:111], v[16:17], v[206:207]
	v_pk_fma_f32 v[210:211], v[80:81], v[20:21], v[210:211]
	v_pk_fma_f32 v[208:209], v[112:113], v[18:19], v[208:209]
	v_pk_fma_f32 v[212:213], v[82:83], v[22:23], v[212:213]
	v_and_b32_e32 v214, 0x7fffffff, v206
	v_and_b32_e32 v215, 0x7fffffff, v207
	v_pk_mul_f32 v[218:219], v[206:207], v[206:207]
	v_pk_fma_f32 v[214:215], v[214:215], s[6:7], 1.0 op_sel_hi:[1,0,0]
	v_pk_mul_f32 v[218:219], v[218:219], s[36:37] op_sel_hi:[1,0]
	v_rcp_f32_e32 v214, v214
	v_rcp_f32_e32 v215, v215
	v_exp_f32_e32 v218, v218
	v_exp_f32_e32 v219, v219
	v_pk_fma_f32 v[216:217], v[214:215], s[24:25], v[186:187] op_sel_hi:[1,0,0]
	v_max_f32_e32 v220, 0, v206
	v_pk_fma_f32 v[216:217], v[214:215], v[216:217], s[28:29] op_sel_hi:[1,1,0]
	v_max_f32_e32 v221, 0, v207
	v_pk_fma_f32 v[216:217], v[214:215], v[216:217], s[30:31] op_sel_hi:[1,1,0]
	s_nop 0
	v_pk_fma_f32 v[216:217], v[214:215], v[216:217], s[34:35] op_sel_hi:[1,1,0]
	s_nop 0
	v_pk_mul_f32 v[216:217], v[214:215], v[216:217]
	s_nop 0
	v_pk_mul_f32 v[216:217], v[218:219], v[216:217]
	s_nop 0
	v_fma_f32 v206, -|v206|, v216, v220
	v_fma_f32 v207, -|v207|, v217, v221
	v_mul_f32_e32 v206, v210, v206
	v_mul_f32_e32 v207, v211, v207
	v_and_b32_e32 v214, 0x7fffffff, v208
	v_and_b32_e32 v215, 0x7fffffff, v209
	v_pk_mul_f32 v[218:219], v[208:209], v[208:209]
	v_pk_fma_f32 v[214:215], v[214:215], s[6:7], 1.0 op_sel_hi:[1,0,0]
	v_pk_mul_f32 v[218:219], v[218:219], s[36:37] op_sel_hi:[1,0]
	v_rcp_f32_e32 v214, v214
	v_rcp_f32_e32 v215, v215
	v_exp_f32_e32 v218, v218
	v_exp_f32_e32 v219, v219
	v_pk_fma_f32 v[216:217], v[214:215], s[24:25], v[186:187] op_sel_hi:[1,0,0]
	v_max_f32_e32 v220, 0, v208
	v_pk_fma_f32 v[216:217], v[214:215], v[216:217], s[28:29] op_sel_hi:[1,1,0]
	v_max_f32_e32 v221, 0, v209
	v_pk_fma_f32 v[216:217], v[214:215], v[216:217], s[30:31] op_sel_hi:[1,1,0]
	s_nop 0
	v_pk_fma_f32 v[216:217], v[214:215], v[216:217], s[34:35] op_sel_hi:[1,1,0]
	s_nop 0
	v_pk_mul_f32 v[216:217], v[214:215], v[216:217]
	s_nop 0
	v_pk_mul_f32 v[216:217], v[218:219], v[216:217]
	s_nop 0
	v_fma_f32 v208, -|v208|, v216, v220
	v_fma_f32 v209, -|v209|, v217, v221
	v_mul_f32_e32 v208, v212, v208
	v_mul_f32_e32 v209, v213, v209
	v_mov_b64_e32 v[218:219], v[152:153]
	v_cvt_pk_bf16_f32 v220, v206, v207
	v_cvt_pk_bf16_f32 v221, v208, v209
	v_lshl_add_u64 v[126:127], s[70:71], 0, v[184:185]
	global_store_dwordx4 v[126:127], v[218:221], off
	s_and_saveexec_b64 s[22:23], s[76:77]
	s_cbranch_execz .Lmy_p5_12
	s_lshr_b32 s18, s16, 6
	s_add_i32 s18, s18, 3
	s_mul_i32 s18, s18, 0x5800
	s_mov_b32 s19, 0
	v_lshlrev_b64 v[214:215], 2, v[182:183]
	v_lshl_add_u64 v[214:215], s[18:19], 0, v[214:215]
	v_lshl_add_u64 v[214:215], s[92:93], 0, v[214:215]
	global_store_dwordx4 v[214:215], v[16:19], off offset:16
	v_lshl_add_u64 v[216:217], v[214:215], 0, s[52:53]
	global_store_dwordx4 v[216:217], v[20:23], off offset:3088
	s_bfe_u32 s18, s16, 0x60008
	s_cmp_eq_u32 s18, 63
	s_cbranch_scc0 .Lmy_p5_12
	s_lshr_b32 s18, s16, 14
	s_lshl_b32 s18, s18, 1
	s_add_i32 s18, s18, 1
	s_mul_i32 s18, s18, 0x5800
	s_mov_b32 s19, 0
	v_lshlrev_b64 v[214:215], 2, v[182:183]
	v_lshl_add_u64 v[214:215], s[18:19], 0, v[214:215]
	v_lshl_add_u64 v[214:215], s[0:1], 0, v[214:215]
	global_store_dwordx4 v[214:215], v[16:19], off offset:16
	v_lshl_add_u64 v[216:217], v[214:215], 0, s[52:53]
	global_store_dwordx4 v[216:217], v[20:23], off offset:3088
.Lmy_p5_12:
	s_or_b64 exec, exec, s[22:23]
	s_mov_b64 exec, -1
	s_andn2_b64 vcc, exec, s[46:47]
	s_mov_b64 s[14:15], -1
	s_cbranch_vccnz .LBB0_1021
	v_readlane_b32 s14, v246, 28
	v_readlane_b32 s15, v246, 29
	s_andn2_b64 vcc, exec, s[14:15]
	s_cbranch_vccnz .LBB0_1020
	s_barrier
	s_branch .LBB0_1020
